# P5 LN-param preload (no per-group vmcnt0) + prompt-attn stagger waves0-3 sleep16
# speedup vs baseline: 1.0029x; 1.0029x over previous
; __device__ __forceinline__ int crow(int r, int hi) { return (r & 3) + 8 * (r >> 2) + 4 * hi; }
; __device__ __forceinline__ void qkt(f32x16& p0, f32x16& p1, const char* Ks, const char* Qs, int r32, int hi) {
; #pragma unroll
;     for (int d0 = 0; d0 < 8; ++d0) { const int cb = (d0 * 16 + hi * 8) * 2;
;         const bf16x8 qv = *reinterpret_cast<const bf16x8*>(Qs + KSWZ(r32, cb));
;         const bf16x8 b0 = *reinterpret_cast<const bf16x8*>(Ks + KSWZ(r32, cb));
;         const bf16x8 b1 = *reinterpret_cast<const bf16x8*>(Ks + KSWZ(32 + r32, cb));
;         p0 = __builtin_amdgcn_mfma_f32_32x32x16_bf16(b0, qv, p0, 0, 0, 0);
;         p1 = __builtin_amdgcn_mfma_f32_32x32x16_bf16(b1, qv, p1, 0, 0, 0); }
; template <int MODE, bool SAMPLE>
; __device__ __forceinline__ void attn_unit(const Params& p, char* lds, int b, int h, int qb) {
;     ...
;         if (wact && j <= jd && var < 2) {
;             const char* Kt = K_lds + buf * 16384; const int vb = vb0 + buf * 16384;
;             f32x16 p0, p1; bf16x8 pa0, pa1, pa2, pa3;
;             if (MODE == 0) {
;                 const float* bt = biasL + j * 64 + 4 * hi;
; #pragma unroll
;                 for (int g = 0; g < 4; ++g) { const f32x4 a = *(const f32x4*)(bt + 8 * g), c = *(const f32x4*)(bt + 32 + 8 * g);
; #pragma unroll
;                     for (int i = 0; i < 4; ++i) { p0[4 * g + i] = a[i]; p1[4 * g + i] = c[i]; } }
;                 qkt(p0, p1, Kt, Qs, r32, hi);
;                 if (j == jd) {
; #pragma unroll
;                     for (int r = 0; r < 16; ++r) { const int kp = j * 64 + crow(r, hi); if (kp > qpos) p0[r] = -1e30f; if (kp + 32 > qpos) p1[r] = -1e30f; } }
.LBB0_685:
	s_cmp_ge_i32 s20, s13
	s_waitcnt lgkmcnt(0)
	s_barrier
	s_cbranch_scc1 .LBB0_693
	v_readfirstlane_b32 s98, v183
	s_cmpk_ge_u32 s98, 0x100
	s_cbranch_scc1 .Lstg_0
	s_sleep 16
.Lstg_0:
	ds_read_b128 v[64:67], v216 offset:256
	ds_read_b128 v[68:71], v216 offset:288
	ds_read_b128 v[80:83], v202 offset:16384
	ds_read_b128 v[72:75], v216 offset:320
	ds_read_b128 v[76:79], v216 offset:352
	v_add_u32_e32 v84, s26, v182
	ds_read_b128 v[220:223], v84
	ds_read_b128 v[224:227], v202 offset:24576
	v_add_u32_e32 v84, s26, v184
	ds_read_b128 v[228:231], v84
	s_waitcnt lgkmcnt(2)
	v_mfma_f32_32x32x16_bf16 v[64:79], v[80:83], v[220:223], v[64:79]
	ds_read_b128 v[80:83], v216 offset:384
	ds_read_b128 v[84:87], v216 offset:416
	ds_read_b128 v[88:91], v216 offset:448
	ds_read_b128 v[92:95], v216 offset:480
	v_add_u32_e32 v161, s26, v185
	s_cmp_lg_u32 s21, s20
	s_waitcnt lgkmcnt(0)
	v_mfma_f32_32x32x16_bf16 v[80:95], v[224:227], v[220:223], v[80:95]
	ds_read_b128 v[220:223], v203 offset:16384
	ds_read_b128 v[224:227], v203 offset:24576
	s_waitcnt lgkmcnt(1)
	v_mfma_f32_32x32x16_bf16 v[64:79], v[220:223], v[228:231], v[64:79]
	ds_read_b128 v[220:223], v204 offset:16384
	s_waitcnt lgkmcnt(1)
	v_mfma_f32_32x32x16_bf16 v[80:95], v[224:227], v[228:231], v[80:95]
	ds_read_b128 v[224:227], v161
	ds_read_b128 v[228:231], v204 offset:24576
	v_add_u32_e32 v161, s26, v186
	ds_read_b128 v[232:235], v161
	v_add_u32_e32 v161, s26, v187
	s_waitcnt lgkmcnt(2)
	v_mfma_f32_32x32x16_bf16 v[64:79], v[220:223], v[224:227], v[64:79]
	s_waitcnt lgkmcnt(1)
	v_mfma_f32_32x32x16_bf16 v[80:95], v[228:231], v[224:227], v[80:95]
	ds_read_b128 v[220:223], v205 offset:16384
	ds_read_b128 v[224:227], v205 offset:24576
	s_waitcnt lgkmcnt(1)
	v_mfma_f32_32x32x16_bf16 v[64:79], v[220:223], v[232:235], v[64:79]
	ds_read_b128 v[220:223], v206 offset:16384
	s_waitcnt lgkmcnt(1)
	v_mfma_f32_32x32x16_bf16 v[80:95], v[224:227], v[232:235], v[80:95]
	ds_read_b128 v[224:227], v161
	ds_read_b128 v[228:231], v206 offset:24576
	v_add_u32_e32 v161, s26, v188
	ds_read_b128 v[232:235], v161
	v_add_u32_e32 v161, s26, v189
	s_waitcnt lgkmcnt(2)
	v_mfma_f32_32x32x16_bf16 v[64:79], v[220:223], v[224:227], v[64:79]
	s_waitcnt lgkmcnt(1)
	v_mfma_f32_32x32x16_bf16 v[80:95], v[228:231], v[224:227], v[80:95]
	ds_read_b128 v[220:223], v207 offset:16384
	ds_read_b128 v[224:227], v207 offset:24576
	s_waitcnt lgkmcnt(1)
	v_mfma_f32_32x32x16_bf16 v[64:79], v[220:223], v[232:235], v[64:79]
	ds_read_b128 v[220:223], v208 offset:16384
	s_waitcnt lgkmcnt(1)
	v_mfma_f32_32x32x16_bf16 v[80:95], v[224:227], v[232:235], v[80:95]
	ds_read_b128 v[224:227], v161
	ds_read_b128 v[228:231], v208 offset:24576
	v_add_u32_e32 v161, s26, v190
	ds_read_b128 v[232:235], v161
	s_waitcnt lgkmcnt(2)
	v_mfma_f32_32x32x16_bf16 v[64:79], v[220:223], v[224:227], v[64:79]
	s_waitcnt lgkmcnt(1)
	v_mfma_f32_32x32x16_bf16 v[80:95], v[228:231], v[224:227], v[80:95]
	ds_read_b128 v[220:223], v209 offset:16384
	ds_read_b128 v[224:227], v209 offset:24576
	s_waitcnt lgkmcnt(1)
	v_mfma_f32_32x32x16_bf16 v[64:79], v[220:223], v[232:235], v[64:79]
	s_waitcnt lgkmcnt(0)
	v_mfma_f32_32x32x16_bf16 v[80:95], v[224:227], v[232:235], v[80:95]
	s_cbranch_scc1 .LBB0_688
	v_add_u32_e32 v161, s16, v218
	v_add_u32_e32 v221, 0x60, v161
	v_add_u32_e32 v220, 64, v161
	v_cmp_le_i32_e32 vcc, v221, v215
	s_nop 6
	v_cndmask_b32_e32 v80, v214, v80, vcc
	v_cmp_lt_i32_e32 vcc, v220, v215
	s_nop 1
	v_cndmask_b32_e32 v65, v214, v65, vcc
	v_cmp_le_i32_e32 vcc, v220, v215
	v_add_u32_e32 v220, 0x61, v161
	s_nop 0
	v_cndmask_b32_e32 v64, v214, v64, vcc
	v_cmp_le_i32_e32 vcc, v220, v215
	v_add_u32_e32 v220, 0x42, v161
	s_nop 0
	v_cndmask_b32_e32 v81, v214, v81, vcc
	v_cmp_le_i32_e32 vcc, v220, v215
	v_add_u32_e32 v220, 0x62, v161
	s_nop 0
	v_cndmask_b32_e32 v66, v214, v66, vcc
	v_cmp_le_i32_e32 vcc, v220, v215
	v_add_u32_e32 v220, 0x43, v161
	s_nop 0
	v_cndmask_b32_e32 v82, v214, v82, vcc
	v_cmp_le_i32_e32 vcc, v220, v215
	v_add_u32_e32 v220, 0x63, v161
	s_nop 0
	v_cndmask_b32_e32 v67, v214, v67, vcc
	v_cmp_le_i32_e32 vcc, v220, v215
	v_add_u32_e32 v220, 0x48, v161
	s_nop 0
	v_cndmask_b32_e32 v83, v214, v83, vcc
	v_cmp_le_i32_e32 vcc, v220, v215
	v_add_u32_e32 v220, 0x68, v161
	s_nop 0
	v_cndmask_b32_e32 v68, v214, v68, vcc
	v_cmp_le_i32_e32 vcc, v220, v215
	v_add_u32_e32 v220, 0x49, v161
	s_nop 0
	v_cndmask_b32_e32 v84, v214, v84, vcc
	v_cmp_le_i32_e32 vcc, v220, v215
	v_add_u32_e32 v220, 0x69, v161
	s_nop 0
	v_cndmask_b32_e32 v69, v214, v69, vcc
	v_cmp_le_i32_e32 vcc, v220, v215
	v_add_u32_e32 v220, 0x4a, v161
	s_nop 0
	v_cndmask_b32_e32 v85, v214, v85, vcc
	v_cmp_le_i32_e32 vcc, v220, v215
	v_add_u32_e32 v220, 0x6a, v161
	s_nop 0
	v_cndmask_b32_e32 v70, v214, v70, vcc
	v_cmp_le_i32_e32 vcc, v220, v215
	v_add_u32_e32 v220, 0x4b, v161
	s_nop 0
	v_cndmask_b32_e32 v86, v214, v86, vcc
	v_cmp_le_i32_e32 vcc, v220, v215
	v_add_u32_e32 v220, 0x6b, v161
	s_nop 0
	v_cndmask_b32_e32 v71, v214, v71, vcc
	v_cmp_le_i32_e32 vcc, v220, v215
	v_add_u32_e32 v220, 0x50, v161
	s_nop 0
	v_cndmask_b32_e32 v87, v214, v87, vcc
	v_cmp_le_i32_e32 vcc, v220, v215
	v_add_u32_e32 v220, 0x70, v161
	s_nop 0
	v_cndmask_b32_e32 v72, v214, v72, vcc
	v_cmp_le_i32_e32 vcc, v220, v215
	v_add_u32_e32 v220, 0x51, v161
	s_nop 0
	v_cndmask_b32_e32 v88, v214, v88, vcc
	v_cmp_le_i32_e32 vcc, v220, v215
	v_add_u32_e32 v220, 0x71, v161
	s_nop 0
	v_cndmask_b32_e32 v73, v214, v73, vcc
	v_cmp_le_i32_e32 vcc, v220, v215
	v_add_u32_e32 v220, 0x52, v161
	s_nop 0
	v_cndmask_b32_e32 v89, v214, v89, vcc
	v_cmp_le_i32_e32 vcc, v220, v215
	v_add_u32_e32 v220, 0x72, v161
	s_nop 0
	v_cndmask_b32_e32 v74, v214, v74, vcc
	v_cmp_le_i32_e32 vcc, v220, v215
	v_add_u32_e32 v220, 0x53, v161
	s_nop 0
	v_cndmask_b32_e32 v90, v214, v90, vcc
	v_cmp_le_i32_e32 vcc, v220, v215
	v_add_u32_e32 v220, 0x73, v161
	s_nop 0
	v_cndmask_b32_e32 v75, v214, v75, vcc
	v_cmp_le_i32_e32 vcc, v220, v215
	v_add_u32_e32 v220, 0x58, v161
	s_nop 0
	v_cndmask_b32_e32 v91, v214, v91, vcc
	v_cmp_le_i32_e32 vcc, v220, v215
	v_add_u32_e32 v220, 0x78, v161
	s_nop 0
	v_cndmask_b32_e32 v76, v214, v76, vcc
	v_cmp_le_i32_e32 vcc, v220, v215
	v_add_u32_e32 v220, 0x59, v161
	s_nop 0
	v_cndmask_b32_e32 v92, v214, v92, vcc
	v_cmp_le_i32_e32 vcc, v220, v215
	v_add_u32_e32 v220, 0x79, v161
	s_nop 0
	v_cndmask_b32_e32 v77, v214, v77, vcc
	v_cmp_le_i32_e32 vcc, v220, v215
	v_add_u32_e32 v220, 0x5a, v161
	s_nop 0
	v_cndmask_b32_e32 v93, v214, v93, vcc
	v_cmp_le_i32_e32 vcc, v220, v215
	v_add_u32_e32 v220, 0x7a, v161
	s_nop 0
	v_cndmask_b32_e32 v78, v214, v78, vcc
	v_cmp_le_i32_e32 vcc, v220, v215
	v_add_u32_e32 v220, 0x5b, v161
	v_add_u32_e32 v161, 0x7b, v161
	v_cndmask_b32_e32 v94, v214, v94, vcc
	v_cmp_le_i32_e32 vcc, v220, v215
	s_nop 1
	v_cndmask_b32_e32 v79, v214, v79, vcc
	v_cmp_le_i32_e32 vcc, v161, v215
	s_nop 1
	v_cndmask_b32_e32 v95, v214, v95, vcc

; __device__ __forceinline__ int crow(int r, int hi) { return (r & 3) + 8 * (r >> 2) + 4 * hi; }
; __device__ __forceinline__ void qkt(f32x16& p0, f32x16& p1, const char* Ks, const char* Qs, int r32, int hi) {
; #pragma unroll
;     for (int d0 = 0; d0 < 8; ++d0) { const int cb = (d0 * 16 + hi * 8) * 2;
;         const bf16x8 qv = *reinterpret_cast<const bf16x8*>(Qs + KSWZ(r32, cb));
;         const bf16x8 b0 = *reinterpret_cast<const bf16x8*>(Ks + KSWZ(r32, cb));
;         const bf16x8 b1 = *reinterpret_cast<const bf16x8*>(Ks + KSWZ(32 + r32, cb));
;         p0 = __builtin_amdgcn_mfma_f32_32x32x16_bf16(b0, qv, p0, 0, 0, 0);
;         p1 = __builtin_amdgcn_mfma_f32_32x32x16_bf16(b1, qv, p1, 0, 0, 0); }
; template <int MODE, bool SAMPLE>
; __device__ __forceinline__ void attn_unit(const Params& p, char* lds, int b, int h, int qb) {
;     ...
;         if (wact && j <= jd && var < 2) {
;             const char* Kt = K_lds + buf * 16384; const int vb = vb0 + buf * 16384;
;             f32x16 p0, p1; bf16x8 pa0, pa1, pa2, pa3;
;             if (MODE == 0) {
;                 const float* bt = biasL + j * 64 + 4 * hi;
; #pragma unroll
;                 for (int g = 0; g < 4; ++g) { const f32x4 a = *(const f32x4*)(bt + 8 * g), c = *(const f32x4*)(bt + 32 + 8 * g);
; #pragma unroll
;                     for (int i = 0; i < 4; ++i) { p0[4 * g + i] = a[i]; p1[4 * g + i] = c[i]; } }
;                 qkt(p0, p1, Kt, Qs, r32, hi);
;                 if (j == jd) {
; #pragma unroll
;                     for (int r = 0; r < 16; ++r) { const int kp = j * 64 + crow(r, hi); if (kp > qpos) p0[r] = -1e30f; if (kp + 32 > qpos) p1[r] = -1e30f; } }
.LBB0_696:
	s_cmp_gt_i32 s20, s13
	s_waitcnt lgkmcnt(0)
	s_barrier
	s_cbranch_scc1 .LBB0_681
	v_readfirstlane_b32 s98, v183
	s_cmpk_ge_u32 s98, 0x100
	s_cbranch_scc1 .Lstg_1
	s_sleep 16
.Lstg_1:
	ds_read_b128 v[64:67], v216
	ds_read_b128 v[68:71], v216 offset:32
	ds_read_b128 v[80:83], v202
	ds_read_b128 v[72:75], v216 offset:64
	ds_read_b128 v[76:79], v216 offset:96
	v_add_u32_e32 v84, s26, v182
	ds_read_b128 v[220:223], v84
	ds_read_b128 v[224:227], v202 offset:8192
	v_add_u32_e32 v84, s26, v184
	ds_read_b128 v[228:231], v84
	s_waitcnt lgkmcnt(2)
	v_mfma_f32_32x32x16_bf16 v[64:79], v[80:83], v[220:223], v[64:79]
	ds_read_b128 v[80:83], v216 offset:128
	ds_read_b128 v[84:87], v216 offset:160
	ds_read_b128 v[88:91], v216 offset:192
	ds_read_b128 v[92:95], v216 offset:224
	v_add_u32_e32 v161, s26, v185
	s_cmp_lg_u32 s13, s20
	s_waitcnt lgkmcnt(0)
	v_mfma_f32_32x32x16_bf16 v[80:95], v[224:227], v[220:223], v[80:95]
	ds_read_b128 v[220:223], v203
	ds_read_b128 v[224:227], v203 offset:8192
	s_waitcnt lgkmcnt(1)
	v_mfma_f32_32x32x16_bf16 v[64:79], v[220:223], v[228:231], v[64:79]
	ds_read_b128 v[220:223], v204
	s_waitcnt lgkmcnt(1)
	v_mfma_f32_32x32x16_bf16 v[80:95], v[224:227], v[228:231], v[80:95]
	ds_read_b128 v[224:227], v161
	ds_read_b128 v[228:231], v204 offset:8192
	v_add_u32_e32 v161, s26, v186
	ds_read_b128 v[232:235], v161
	v_add_u32_e32 v161, s26, v187
	s_waitcnt lgkmcnt(2)
	v_mfma_f32_32x32x16_bf16 v[64:79], v[220:223], v[224:227], v[64:79]
	s_waitcnt lgkmcnt(1)
	v_mfma_f32_32x32x16_bf16 v[80:95], v[228:231], v[224:227], v[80:95]
	ds_read_b128 v[220:223], v205
	ds_read_b128 v[224:227], v205 offset:8192
	s_waitcnt lgkmcnt(1)
	v_mfma_f32_32x32x16_bf16 v[64:79], v[220:223], v[232:235], v[64:79]
	ds_read_b128 v[220:223], v206
	s_waitcnt lgkmcnt(1)
	v_mfma_f32_32x32x16_bf16 v[80:95], v[224:227], v[232:235], v[80:95]
	ds_read_b128 v[224:227], v161
	ds_read_b128 v[228:231], v206 offset:8192
	v_add_u32_e32 v161, s26, v188
	ds_read_b128 v[232:235], v161
	v_add_u32_e32 v161, s26, v189
	s_waitcnt lgkmcnt(2)
	v_mfma_f32_32x32x16_bf16 v[64:79], v[220:223], v[224:227], v[64:79]
	s_waitcnt lgkmcnt(1)
	v_mfma_f32_32x32x16_bf16 v[80:95], v[228:231], v[224:227], v[80:95]
	ds_read_b128 v[220:223], v207
	ds_read_b128 v[224:227], v207 offset:8192
	s_waitcnt lgkmcnt(1)
	v_mfma_f32_32x32x16_bf16 v[64:79], v[220:223], v[232:235], v[64:79]
	ds_read_b128 v[220:223], v208
	s_waitcnt lgkmcnt(1)
	v_mfma_f32_32x32x16_bf16 v[80:95], v[224:227], v[232:235], v[80:95]
	ds_read_b128 v[224:227], v161
	ds_read_b128 v[228:231], v208 offset:8192
	v_add_u32_e32 v161, s26, v190
	ds_read_b128 v[232:235], v161
	s_waitcnt lgkmcnt(2)
	v_mfma_f32_32x32x16_bf16 v[64:79], v[220:223], v[224:227], v[64:79]
	s_waitcnt lgkmcnt(1)
	v_mfma_f32_32x32x16_bf16 v[80:95], v[228:231], v[224:227], v[80:95]
	ds_read_b128 v[220:223], v209
	ds_read_b128 v[224:227], v209 offset:8192
	s_waitcnt lgkmcnt(1)
	v_mfma_f32_32x32x16_bf16 v[64:79], v[220:223], v[232:235], v[64:79]
	s_waitcnt lgkmcnt(0)
	v_mfma_f32_32x32x16_bf16 v[80:95], v[224:227], v[232:235], v[80:95]
	s_cbranch_scc1 .LBB0_699
	v_add_u32_e32 v161, s16, v218
	v_add_u32_e32 v220, 32, v161
	v_cmp_le_i32_e32 vcc, v220, v215
	v_add_u32_e32 v220, 33, v161
	s_nop 6
	v_cndmask_b32_e32 v80, v214, v80, vcc
	v_cmp_lt_i32_e32 vcc, v161, v215
	s_nop 1
	v_cndmask_b32_e32 v65, v214, v65, vcc
	v_cmp_le_i32_e32 vcc, v161, v215
	s_nop 1
	v_cndmask_b32_e32 v64, v214, v64, vcc
	v_cmp_le_i32_e32 vcc, v220, v215
	v_add_u32_e32 v220, 2, v161
	s_nop 0
	v_cndmask_b32_e32 v81, v214, v81, vcc
	v_cmp_le_i32_e32 vcc, v220, v215
	v_add_u32_e32 v220, 34, v161
	s_nop 0
	v_cndmask_b32_e32 v66, v214, v66, vcc
	v_cmp_le_i32_e32 vcc, v220, v215
	v_add_u32_e32 v220, 3, v161
	s_nop 0
	v_cndmask_b32_e32 v82, v214, v82, vcc
	v_cmp_le_i32_e32 vcc, v220, v215
	v_add_u32_e32 v220, 35, v161
	s_nop 0
	v_cndmask_b32_e32 v67, v214, v67, vcc
	v_cmp_le_i32_e32 vcc, v220, v215
	v_add_u32_e32 v220, 8, v161
	s_nop 0
	v_cndmask_b32_e32 v83, v214, v83, vcc
	v_cmp_le_i32_e32 vcc, v220, v215
	v_add_u32_e32 v220, 40, v161
	s_nop 0
	v_cndmask_b32_e32 v68, v214, v68, vcc
	v_cmp_le_i32_e32 vcc, v220, v215
	v_add_u32_e32 v220, 9, v161
	s_nop 0
	v_cndmask_b32_e32 v84, v214, v84, vcc
	v_cmp_le_i32_e32 vcc, v220, v215
	v_add_u32_e32 v220, 41, v161
	s_nop 0
	v_cndmask_b32_e32 v69, v214, v69, vcc
	v_cmp_le_i32_e32 vcc, v220, v215
	v_add_u32_e32 v220, 10, v161
	s_nop 0
	v_cndmask_b32_e32 v85, v214, v85, vcc
	v_cmp_le_i32_e32 vcc, v220, v215
	v_add_u32_e32 v220, 42, v161
	s_nop 0
	v_cndmask_b32_e32 v70, v214, v70, vcc
	v_cmp_le_i32_e32 vcc, v220, v215
	v_add_u32_e32 v220, 11, v161
	s_nop 0
	v_cndmask_b32_e32 v86, v214, v86, vcc
	v_cmp_le_i32_e32 vcc, v220, v215
	v_add_u32_e32 v220, 43, v161
	s_nop 0
	v_cndmask_b32_e32 v71, v214, v71, vcc
	v_cmp_le_i32_e32 vcc, v220, v215
	v_add_u32_e32 v220, 16, v161
	s_nop 0
	v_cndmask_b32_e32 v87, v214, v87, vcc
	v_cmp_le_i32_e32 vcc, v220, v215
	v_add_u32_e32 v220, 48, v161
	s_nop 0
	v_cndmask_b32_e32 v72, v214, v72, vcc
	v_cmp_le_i32_e32 vcc, v220, v215
	v_add_u32_e32 v220, 17, v161
	s_nop 0
	v_cndmask_b32_e32 v88, v214, v88, vcc
	v_cmp_le_i32_e32 vcc, v220, v215
	v_add_u32_e32 v220, 49, v161
	s_nop 0
	v_cndmask_b32_e32 v73, v214, v73, vcc
	v_cmp_le_i32_e32 vcc, v220, v215
	v_add_u32_e32 v220, 18, v161
	s_nop 0
	v_cndmask_b32_e32 v89, v214, v89, vcc
	v_cmp_le_i32_e32 vcc, v220, v215
	v_add_u32_e32 v220, 50, v161
	s_nop 0
	v_cndmask_b32_e32 v74, v214, v74, vcc
	v_cmp_le_i32_e32 vcc, v220, v215
	v_add_u32_e32 v220, 19, v161
	s_nop 0
	v_cndmask_b32_e32 v90, v214, v90, vcc
	v_cmp_le_i32_e32 vcc, v220, v215
	v_add_u32_e32 v220, 51, v161
	s_nop 0
	v_cndmask_b32_e32 v75, v214, v75, vcc
	v_cmp_le_i32_e32 vcc, v220, v215
	v_add_u32_e32 v220, 24, v161
	s_nop 0
	v_cndmask_b32_e32 v91, v214, v91, vcc
	v_cmp_le_i32_e32 vcc, v220, v215
	v_add_u32_e32 v220, 56, v161
	s_nop 0
	v_cndmask_b32_e32 v76, v214, v76, vcc
	v_cmp_le_i32_e32 vcc, v220, v215
	v_add_u32_e32 v220, 25, v161
	s_nop 0
	v_cndmask_b32_e32 v92, v214, v92, vcc
	v_cmp_le_i32_e32 vcc, v220, v215
	v_add_u32_e32 v220, 57, v161
	s_nop 0
	v_cndmask_b32_e32 v77, v214, v77, vcc
	v_cmp_le_i32_e32 vcc, v220, v215
	v_add_u32_e32 v220, 26, v161
	s_nop 0
	v_cndmask_b32_e32 v93, v214, v93, vcc
	v_cmp_le_i32_e32 vcc, v220, v215
	v_add_u32_e32 v220, 58, v161
	s_nop 0
	v_cndmask_b32_e32 v78, v214, v78, vcc
	v_cmp_le_i32_e32 vcc, v220, v215
	v_add_u32_e32 v220, 27, v161
	v_add_u32_e32 v161, 59, v161
	v_cndmask_b32_e32 v94, v214, v94, vcc
	v_cmp_le_i32_e32 vcc, v220, v215
	s_nop 1
	v_cndmask_b32_e32 v79, v214, v79, vcc
	v_cmp_le_i32_e32 vcc, v161, v215
	s_nop 1
	v_cndmask_b32_e32 v95, v214, v95, vcc

; __device__ __forceinline__ int crow(int r, int hi) { return (r & 3) + 8 * (r >> 2) + 4 * hi; }
; __device__ __forceinline__ void qkt(f32x16& p0, f32x16& p1, const char* Ks, const char* Qs, int r32, int hi) {
; #pragma unroll
;     for (int d0 = 0; d0 < 8; ++d0) { const int cb = (d0 * 16 + hi * 8) * 2;
;         const bf16x8 qv = *reinterpret_cast<const bf16x8*>(Qs + KSWZ(r32, cb));
;         const bf16x8 b0 = *reinterpret_cast<const bf16x8*>(Ks + KSWZ(r32, cb));
;         const bf16x8 b1 = *reinterpret_cast<const bf16x8*>(Ks + KSWZ(32 + r32, cb));
;         p0 = __builtin_amdgcn_mfma_f32_32x32x16_bf16(b0, qv, p0, 0, 0, 0);
;         p1 = __builtin_amdgcn_mfma_f32_32x32x16_bf16(b1, qv, p1, 0, 0, 0); }
; template <int MODE, bool SAMPLE>
; __device__ __forceinline__ void attn_unit(const Params& p, char* lds, int b, int h, int qb) {
;     ...
;             } else {
;                 p0 = f32x16{}; p1 = f32x16{};
;                 qkt(p0, p1, Kt, Qs, r32, hi);
;                 if (j == jd) {
; #pragma unroll
;                     for (int r = 0; r < 16; ++r) { const int kp = j * 64 + crow(r, hi); if (kp >= qpos) p0[r] = -1e30f; if (kp + 32 >= qpos) p1[r] = -1e30f; } }
.LBB0_711:
	s_cmp_ge_u32 s33, s13
	s_waitcnt lgkmcnt(0)
	s_barrier
	s_cbranch_scc1 .LBB0_715
	v_readfirstlane_b32 s98, v183
	s_cmpk_ge_u32 s98, 0x100
	s_cbranch_scc1 .Lstg_2
	s_sleep 16
.Lstg_2:
	ds_read_b128 v[64:67], v202 offset:16384
	ds_read_b128 v[84:87], v202 offset:24576
	v_add_u32_e32 v68, s12, v182
	ds_read_b128 v[80:83], v68
	ds_read_b128 v[216:219], v203 offset:16384
	v_add_u32_e32 v147, s12, v184
	ds_read_b128 v[220:223], v147
	v_add_u32_e32 v147, s12, v185
	s_cmp_lg_u32 s6, s33
	s_waitcnt lgkmcnt(2)
	v_mfma_f32_32x32x16_bf16 v[64:79], v[64:67], v[80:83], 0
	s_waitcnt lgkmcnt(0)
	v_mfma_f32_32x32x16_bf16 v[64:79], v[216:219], v[220:223], v[64:79]
	ds_read_b128 v[216:219], v203 offset:24576
	v_mfma_f32_32x32x16_bf16 v[80:95], v[84:87], v[80:83], 0
	s_waitcnt lgkmcnt(0)
	v_mfma_f32_32x32x16_bf16 v[80:95], v[216:219], v[220:223], v[80:95]
	ds_read_b128 v[216:219], v204 offset:16384
	ds_read_b128 v[220:223], v147
	v_add_u32_e32 v147, s12, v186
	s_waitcnt lgkmcnt(0)
	v_mfma_f32_32x32x16_bf16 v[64:79], v[216:219], v[220:223], v[64:79]
	ds_read_b128 v[216:219], v204 offset:24576
	s_waitcnt lgkmcnt(0)
	v_mfma_f32_32x32x16_bf16 v[80:95], v[216:219], v[220:223], v[80:95]
	ds_read_b128 v[216:219], v205 offset:16384
	ds_read_b128 v[220:223], v147
	v_add_u32_e32 v147, s12, v187
	s_waitcnt lgkmcnt(0)
	v_mfma_f32_32x32x16_bf16 v[64:79], v[216:219], v[220:223], v[64:79]
	ds_read_b128 v[216:219], v205 offset:24576
	s_waitcnt lgkmcnt(0)
	v_mfma_f32_32x32x16_bf16 v[80:95], v[216:219], v[220:223], v[80:95]
	ds_read_b128 v[216:219], v206 offset:16384
	ds_read_b128 v[220:223], v147
	v_add_u32_e32 v147, s12, v188
	s_waitcnt lgkmcnt(0)
	v_mfma_f32_32x32x16_bf16 v[64:79], v[216:219], v[220:223], v[64:79]
	ds_read_b128 v[216:219], v206 offset:24576
	s_waitcnt lgkmcnt(0)
	v_mfma_f32_32x32x16_bf16 v[80:95], v[216:219], v[220:223], v[80:95]
	ds_read_b128 v[216:219], v207 offset:16384
	ds_read_b128 v[220:223], v147
	v_add_u32_e32 v147, s12, v189
	s_waitcnt lgkmcnt(0)
	v_mfma_f32_32x32x16_bf16 v[64:79], v[216:219], v[220:223], v[64:79]
	ds_read_b128 v[216:219], v207 offset:24576
	s_waitcnt lgkmcnt(0)
	v_mfma_f32_32x32x16_bf16 v[80:95], v[216:219], v[220:223], v[80:95]
	ds_read_b128 v[216:219], v208 offset:16384
	ds_read_b128 v[220:223], v147
	v_add_u32_e32 v147, s12, v190
	s_waitcnt lgkmcnt(0)
	v_mfma_f32_32x32x16_bf16 v[64:79], v[216:219], v[220:223], v[64:79]
	ds_read_b128 v[216:219], v208 offset:24576
	s_waitcnt lgkmcnt(0)
	v_mfma_f32_32x32x16_bf16 v[80:95], v[216:219], v[220:223], v[80:95]
	ds_read_b128 v[216:219], v209 offset:16384
	ds_read_b128 v[220:223], v147
	s_waitcnt lgkmcnt(0)
	v_mfma_f32_32x32x16_bf16 v[64:79], v[216:219], v[220:223], v[64:79]
	ds_read_b128 v[216:219], v209 offset:24576
	s_waitcnt lgkmcnt(0)
	v_mfma_f32_32x32x16_bf16 v[80:95], v[216:219], v[220:223], v[80:95]
	s_cbranch_scc1 .LBB0_714
	s_or_b64 s[80:81], s[76:77], s[72:73]
	s_nop 6
	v_cndmask_b32_e64 v78, v214, v78, s[80:81]
	s_or_b64 s[80:81], s[80:81], s[68:69]
	v_cndmask_b32_e64 v77, v214, v77, s[80:81]
	s_or_b64 s[80:81], s[80:81], s[64:65]
	v_cndmask_b32_e64 v76, v214, v76, s[80:81]
	s_or_b64 s[80:81], s[80:81], s[60:61]
	v_cndmask_b32_e64 v75, v214, v75, s[80:81]
	s_or_b64 s[80:81], s[80:81], s[56:57]
	v_cndmask_b32_e64 v74, v214, v74, s[80:81]
	s_or_b64 s[80:81], s[80:81], s[52:53]
	v_cndmask_b32_e64 v73, v214, v73, s[80:81]
	s_or_b64 s[80:81], s[80:81], s[48:49]
	v_cndmask_b32_e64 v72, v214, v72, s[80:81]
	s_or_b64 s[80:81], s[80:81], s[44:45]
	v_cndmask_b32_e64 v71, v214, v71, s[80:81]
	s_or_b64 s[80:81], s[80:81], s[40:41]
	v_cndmask_b32_e64 v70, v214, v70, s[80:81]
	s_or_b64 s[80:81], s[80:81], s[36:37]
	v_cndmask_b32_e64 v69, v214, v69, s[80:81]
	s_or_b64 s[80:81], s[80:81], s[30:31]
	v_cndmask_b32_e64 v68, v214, v68, s[80:81]
	s_or_b64 s[80:81], s[80:81], s[26:27]
	v_cndmask_b32_e64 v67, v214, v67, s[80:81]
	s_or_b64 s[80:81], s[80:81], s[22:23]
	v_cndmask_b32_e64 v66, v214, v66, s[80:81]
	s_or_b64 s[80:81], s[80:81], s[18:19]
	v_cndmask_b32_e64 v65, v214, v65, s[80:81]
	s_or_b64 s[80:81], s[80:81], vcc
	v_cndmask_b32_e64 v64, v214, v64, s[80:81]
	s_or_b64 s[80:81], s[78:79], s[74:75]
	v_cndmask_b32_e64 v94, v214, v94, s[80:81]
	s_or_b64 s[80:81], s[80:81], s[70:71]
	v_cndmask_b32_e64 v93, v214, v93, s[80:81]
	s_or_b64 s[80:81], s[80:81], s[66:67]
	v_cndmask_b32_e64 v92, v214, v92, s[80:81]
	s_or_b64 s[80:81], s[80:81], s[62:63]
	v_cndmask_b32_e64 v91, v214, v91, s[80:81]
	s_or_b64 s[80:81], s[80:81], s[58:59]
	v_cndmask_b32_e64 v90, v214, v90, s[80:81]
	s_or_b64 s[80:81], s[80:81], s[54:55]
	v_cndmask_b32_e64 v89, v214, v89, s[80:81]
	s_or_b64 s[80:81], s[80:81], s[50:51]
	v_cndmask_b32_e64 v88, v214, v88, s[80:81]
	s_or_b64 s[80:81], s[80:81], s[46:47]
	v_cndmask_b32_e64 v87, v214, v87, s[80:81]
	s_or_b64 s[80:81], s[80:81], s[42:43]
	v_cndmask_b32_e64 v86, v214, v86, s[80:81]
	s_or_b64 s[80:81], s[80:81], s[38:39]
	v_cndmask_b32_e64 v85, v214, v85, s[80:81]
	s_or_b64 s[80:81], s[80:81], s[34:35]
	v_cndmask_b32_e64 v84, v214, v84, s[80:81]
	s_or_b64 s[80:81], s[80:81], s[28:29]
	v_cndmask_b32_e64 v83, v214, v83, s[80:81]
	s_or_b64 s[80:81], s[80:81], s[24:25]
	v_cndmask_b32_e64 v82, v214, v82, s[80:81]
	s_or_b64 s[80:81], s[80:81], s[20:21]
	v_cndmask_b32_e64 v81, v214, v81, s[80:81]
	s_or_b64 s[80:81], s[80:81], s[0:1]
	v_cndmask_b32_e64 v79, v214, v79, s[76:77]
	v_cndmask_b32_e64 v95, v214, v95, s[78:79]
	v_cndmask_b32_e64 v80, v214, v80, s[80:81]

; __device__ __forceinline__ int crow(int r, int hi) { return (r & 3) + 8 * (r >> 2) + 4 * hi; }
; __device__ __forceinline__ void qkt(f32x16& p0, f32x16& p1, const char* Ks, const char* Qs, int r32, int hi) {
; #pragma unroll
;     for (int d0 = 0; d0 < 8; ++d0) { const int cb = (d0 * 16 + hi * 8) * 2;
;         const bf16x8 qv = *reinterpret_cast<const bf16x8*>(Qs + KSWZ(r32, cb));
;         const bf16x8 b0 = *reinterpret_cast<const bf16x8*>(Ks + KSWZ(r32, cb));
;         const bf16x8 b1 = *reinterpret_cast<const bf16x8*>(Ks + KSWZ(32 + r32, cb));
;         p0 = __builtin_amdgcn_mfma_f32_32x32x16_bf16(b0, qv, p0, 0, 0, 0);
;         p1 = __builtin_amdgcn_mfma_f32_32x32x16_bf16(b1, qv, p1, 0, 0, 0); }
; template <int MODE, bool SAMPLE>
; __device__ __forceinline__ void attn_unit(const Params& p, char* lds, int b, int h, int qb) {
;     ...
;             } else {
;                 p0 = f32x16{}; p1 = f32x16{};
;                 qkt(p0, p1, Kt, Qs, r32, hi);
;                 if (j == jd) {
; #pragma unroll
;                     for (int r = 0; r < 16; ++r) { const int kp = j * 64 + crow(r, hi); if (kp >= qpos) p0[r] = -1e30f; if (kp + 32 >= qpos) p1[r] = -1e30f; } }
.LBB0_718:
	s_cmp_gt_u32 s33, s13
	s_waitcnt lgkmcnt(0)
	s_barrier
	s_cbranch_scc1 .LBB0_707
	v_readfirstlane_b32 s98, v183
	s_cmpk_ge_u32 s98, 0x100
	s_cbranch_scc1 .Lstg_3
	s_sleep 16
.Lstg_3:
	ds_read_b128 v[64:67], v202
	ds_read_b128 v[84:87], v202 offset:8192
	v_add_u32_e32 v68, s12, v182
	ds_read_b128 v[80:83], v68
	ds_read_b128 v[216:219], v203
	v_add_u32_e32 v147, s12, v184
	ds_read_b128 v[220:223], v147
	v_add_u32_e32 v147, s12, v185
	s_cmp_lg_u32 s13, s33
	s_waitcnt lgkmcnt(2)
	v_mfma_f32_32x32x16_bf16 v[64:79], v[64:67], v[80:83], 0
	s_waitcnt lgkmcnt(0)
	v_mfma_f32_32x32x16_bf16 v[64:79], v[216:219], v[220:223], v[64:79]
	ds_read_b128 v[216:219], v203 offset:8192
	v_mfma_f32_32x32x16_bf16 v[80:95], v[84:87], v[80:83], 0
	s_waitcnt lgkmcnt(0)
	v_mfma_f32_32x32x16_bf16 v[80:95], v[216:219], v[220:223], v[80:95]
	ds_read_b128 v[216:219], v204
	ds_read_b128 v[220:223], v147
	v_add_u32_e32 v147, s12, v186
	s_waitcnt lgkmcnt(0)
	v_mfma_f32_32x32x16_bf16 v[64:79], v[216:219], v[220:223], v[64:79]
	ds_read_b128 v[216:219], v204 offset:8192
	s_waitcnt lgkmcnt(0)
	v_mfma_f32_32x32x16_bf16 v[80:95], v[216:219], v[220:223], v[80:95]
	ds_read_b128 v[216:219], v205
	ds_read_b128 v[220:223], v147
	v_add_u32_e32 v147, s12, v187
	s_waitcnt lgkmcnt(0)
	v_mfma_f32_32x32x16_bf16 v[64:79], v[216:219], v[220:223], v[64:79]
	ds_read_b128 v[216:219], v205 offset:8192
	s_waitcnt lgkmcnt(0)
	v_mfma_f32_32x32x16_bf16 v[80:95], v[216:219], v[220:223], v[80:95]
	ds_read_b128 v[216:219], v206
	ds_read_b128 v[220:223], v147
	v_add_u32_e32 v147, s12, v188
	s_waitcnt lgkmcnt(0)
	v_mfma_f32_32x32x16_bf16 v[64:79], v[216:219], v[220:223], v[64:79]
	ds_read_b128 v[216:219], v206 offset:8192
	s_waitcnt lgkmcnt(0)
	v_mfma_f32_32x32x16_bf16 v[80:95], v[216:219], v[220:223], v[80:95]
	ds_read_b128 v[216:219], v207
	ds_read_b128 v[220:223], v147
	v_add_u32_e32 v147, s12, v189
	s_waitcnt lgkmcnt(0)
	v_mfma_f32_32x32x16_bf16 v[64:79], v[216:219], v[220:223], v[64:79]
	ds_read_b128 v[216:219], v207 offset:8192
	s_waitcnt lgkmcnt(0)
	v_mfma_f32_32x32x16_bf16 v[80:95], v[216:219], v[220:223], v[80:95]
	ds_read_b128 v[216:219], v208
	ds_read_b128 v[220:223], v147
	v_add_u32_e32 v147, s12, v190
	s_waitcnt lgkmcnt(0)
	v_mfma_f32_32x32x16_bf16 v[64:79], v[216:219], v[220:223], v[64:79]
	ds_read_b128 v[216:219], v208 offset:8192
	s_waitcnt lgkmcnt(0)
	v_mfma_f32_32x32x16_bf16 v[80:95], v[216:219], v[220:223], v[80:95]
	ds_read_b128 v[216:219], v209
	ds_read_b128 v[220:223], v147
	s_waitcnt lgkmcnt(0)
	v_mfma_f32_32x32x16_bf16 v[64:79], v[216:219], v[220:223], v[64:79]
	ds_read_b128 v[216:219], v209 offset:8192
	s_waitcnt lgkmcnt(0)
	v_mfma_f32_32x32x16_bf16 v[80:95], v[216:219], v[220:223], v[80:95]
	s_cbranch_scc1 .LBB0_706
	s_or_b64 s[80:81], s[76:77], s[72:73]
	s_nop 6
	v_cndmask_b32_e64 v78, v214, v78, s[80:81]
	s_or_b64 s[80:81], s[80:81], s[68:69]
	v_cndmask_b32_e64 v77, v214, v77, s[80:81]
	s_or_b64 s[80:81], s[80:81], s[64:65]
	v_cndmask_b32_e64 v76, v214, v76, s[80:81]
	s_or_b64 s[80:81], s[80:81], s[60:61]
	v_cndmask_b32_e64 v75, v214, v75, s[80:81]
	s_or_b64 s[80:81], s[80:81], s[56:57]
	v_cndmask_b32_e64 v74, v214, v74, s[80:81]
	s_or_b64 s[80:81], s[80:81], s[52:53]
	v_cndmask_b32_e64 v73, v214, v73, s[80:81]
	s_or_b64 s[80:81], s[80:81], s[48:49]
	v_cndmask_b32_e64 v72, v214, v72, s[80:81]
	s_or_b64 s[80:81], s[80:81], s[44:45]
	v_cndmask_b32_e64 v71, v214, v71, s[80:81]
	s_or_b64 s[80:81], s[80:81], s[40:41]
	v_cndmask_b32_e64 v70, v214, v70, s[80:81]
	s_or_b64 s[80:81], s[80:81], s[36:37]
	v_cndmask_b32_e64 v69, v214, v69, s[80:81]
	s_or_b64 s[80:81], s[80:81], s[30:31]
	v_cndmask_b32_e64 v68, v214, v68, s[80:81]
	s_or_b64 s[80:81], s[80:81], s[26:27]
	v_cndmask_b32_e64 v67, v214, v67, s[80:81]
	s_or_b64 s[80:81], s[80:81], s[22:23]
	v_cndmask_b32_e64 v66, v214, v66, s[80:81]
	s_or_b64 s[80:81], s[80:81], s[18:19]
	v_cndmask_b32_e64 v65, v214, v65, s[80:81]
	s_or_b64 s[80:81], s[80:81], vcc
	v_cndmask_b32_e64 v64, v214, v64, s[80:81]
	s_or_b64 s[80:81], s[78:79], s[74:75]
	v_cndmask_b32_e64 v94, v214, v94, s[80:81]
	s_or_b64 s[80:81], s[80:81], s[70:71]
	v_cndmask_b32_e64 v93, v214, v93, s[80:81]
	s_or_b64 s[80:81], s[80:81], s[66:67]
	v_cndmask_b32_e64 v92, v214, v92, s[80:81]
	s_or_b64 s[80:81], s[80:81], s[62:63]
	v_cndmask_b32_e64 v91, v214, v91, s[80:81]
	s_or_b64 s[80:81], s[80:81], s[58:59]
	v_cndmask_b32_e64 v90, v214, v90, s[80:81]
	s_or_b64 s[80:81], s[80:81], s[54:55]
	v_cndmask_b32_e64 v89, v214, v89, s[80:81]
	s_or_b64 s[80:81], s[80:81], s[50:51]
	v_cndmask_b32_e64 v88, v214, v88, s[80:81]
	s_or_b64 s[80:81], s[80:81], s[46:47]
	v_cndmask_b32_e64 v87, v214, v87, s[80:81]
	s_or_b64 s[80:81], s[80:81], s[42:43]
	v_cndmask_b32_e64 v86, v214, v86, s[80:81]
	s_or_b64 s[80:81], s[80:81], s[38:39]
	v_cndmask_b32_e64 v85, v214, v85, s[80:81]
	s_or_b64 s[80:81], s[80:81], s[34:35]
	v_cndmask_b32_e64 v84, v214, v84, s[80:81]
	s_or_b64 s[80:81], s[80:81], s[28:29]
	v_cndmask_b32_e64 v83, v214, v83, s[80:81]
	s_or_b64 s[80:81], s[80:81], s[24:25]
	v_cndmask_b32_e64 v82, v214, v82, s[80:81]
	s_or_b64 s[80:81], s[80:81], s[20:21]
	v_cndmask_b32_e64 v81, v214, v81, s[80:81]
	s_or_b64 s[80:81], s[80:81], s[0:1]
	v_cndmask_b32_e64 v79, v214, v79, s[76:77]
	v_cndmask_b32_e64 v95, v214, v95, s[78:79]
	v_cndmask_b32_e64 v80, v214, v80, s[80:81]
	s_branch .LBB0_706

; template <int MODE, bool SAMPLE>
; __device__ __forceinline__ void attn_unit(const Params& p, char* lds, int b, int h, int qb) {
;     ...
;         __syncthreads();
;         if (wact && j <= jd && var < 2) {
.LBB0_760:
	s_cmp_ge_i32 s18, s11
	s_waitcnt lgkmcnt(0)
	s_barrier
	s_cbranch_scc1 .LBB0_768
	v_readfirstlane_b32 s98, v183
	s_cmpk_ge_u32 s98, 0x100
	s_cbranch_scc1 .Lstg_4
	s_sleep 16
; __device__ __forceinline__ int crow(int r, int hi) { return (r & 3) + 8 * (r >> 2) + 4 * hi; }
; __device__ __forceinline__ void qkt(f32x16& p0, f32x16& p1, const char* Ks, const char* Qs, int r32, int hi) {
; #pragma unroll
;     for (int d0 = 0; d0 < 8; ++d0) { const int cb = (d0 * 16 + hi * 8) * 2;
;         const bf16x8 qv = *reinterpret_cast<const bf16x8*>(Qs + KSWZ(r32, cb));
;         const bf16x8 b0 = *reinterpret_cast<const bf16x8*>(Ks + KSWZ(r32, cb));
;         const bf16x8 b1 = *reinterpret_cast<const bf16x8*>(Ks + KSWZ(32 + r32, cb));
;         p0 = __builtin_amdgcn_mfma_f32_32x32x16_bf16(b0, qv, p0, 0, 0, 0);
;         p1 = __builtin_amdgcn_mfma_f32_32x32x16_bf16(b1, qv, p1, 0, 0, 0); }
; template <int MODE, bool SAMPLE>
; __device__ __forceinline__ void attn_unit(const Params& p, char* lds, int b, int h, int qb) {
;     ...
;             if (MODE == 0) {
;                 const float* bt = biasL + j * 64 + 4 * hi;
; #pragma unroll
;                 for (int g = 0; g < 4; ++g) { const f32x4 a = *(const f32x4*)(bt + 8 * g), c = *(const f32x4*)(bt + 32 + 8 * g);
; #pragma unroll
;                     for (int i = 0; i < 4; ++i) { p0[4 * g + i] = a[i]; p1[4 * g + i] = c[i]; } }
;                 qkt(p0, p1, Kt, Qs, r32, hi);
;                 if (j == jd) {
; #pragma unroll
;                     for (int r = 0; r < 16; ++r) { const int kp = j * 64 + crow(r, hi); if (kp > qpos) p0[r] = -1e30f; if (kp + 32 > qpos) p1[r] = -1e30f; } }
.Lstg_4:
	v_add_u32_e32 v64, s24, v181
	v_add_u32_e32 v84, 0, v181
	ds_read_b128 v[216:219], v64
	ds_read_b128 v[80:83], v84 offset:16384
	ds_read_b128 v[64:67], v199 offset:256
	ds_read_b128 v[68:71], v199 offset:288
	ds_read_b128 v[72:75], v199 offset:320
	ds_read_b128 v[76:79], v199 offset:352
	ds_read_b128 v[220:223], v84 offset:24576
	v_add_u32_e32 v159, s24, v182
	v_add_u32_e32 v215, s24, v184
	s_waitcnt lgkmcnt(1)
	v_mfma_f32_32x32x16_bf16 v[64:79], v[80:83], v[216:219], v[64:79]
	ds_read_b128 v[80:83], v199 offset:384
	ds_read_b128 v[84:87], v199 offset:416
	ds_read_b128 v[88:91], v199 offset:448
	ds_read_b128 v[92:95], v199 offset:480
	ds_read_b128 v[224:227], v159
	v_add_u32_e32 v159, 0, v182
	s_cmp_lg_u32 s19, s18
	s_waitcnt lgkmcnt(1)
	v_mfma_f32_32x32x16_bf16 v[80:95], v[220:223], v[216:219], v[80:95]
	ds_read_b128 v[216:219], v159 offset:16384
	ds_read_b128 v[220:223], v159 offset:24576
	v_add_u32_e32 v159, 0, v184
	s_waitcnt lgkmcnt(1)
	v_mfma_f32_32x32x16_bf16 v[64:79], v[216:219], v[224:227], v[64:79]
	ds_read_b128 v[216:219], v159 offset:16384
	s_waitcnt lgkmcnt(1)
	v_mfma_f32_32x32x16_bf16 v[80:95], v[220:223], v[224:227], v[80:95]
	ds_read_b128 v[220:223], v215
	v_add_u32_e32 v215, s24, v186
	s_waitcnt lgkmcnt(0)
	v_mfma_f32_32x32x16_bf16 v[64:79], v[216:219], v[220:223], v[64:79]
	ds_read_b128 v[216:219], v159 offset:24576
	v_add_u32_e32 v159, s24, v185
	ds_read_b128 v[224:227], v159
	v_add_u32_e32 v159, 0, v185
	s_waitcnt lgkmcnt(1)
	v_mfma_f32_32x32x16_bf16 v[80:95], v[216:219], v[220:223], v[80:95]
	ds_read_b128 v[216:219], v159 offset:16384
	ds_read_b128 v[220:223], v159 offset:24576
	v_add_u32_e32 v159, 0, v186
	s_waitcnt lgkmcnt(1)
	v_mfma_f32_32x32x16_bf16 v[64:79], v[216:219], v[224:227], v[64:79]
	ds_read_b128 v[216:219], v159 offset:16384
	s_waitcnt lgkmcnt(1)
	v_mfma_f32_32x32x16_bf16 v[80:95], v[220:223], v[224:227], v[80:95]
	ds_read_b128 v[220:223], v215
	v_add_u32_e32 v215, s24, v188
	s_waitcnt lgkmcnt(0)
	v_mfma_f32_32x32x16_bf16 v[64:79], v[216:219], v[220:223], v[64:79]
	ds_read_b128 v[216:219], v159 offset:24576
	v_add_u32_e32 v159, s24, v187
	ds_read_b128 v[224:227], v159
	v_add_u32_e32 v159, 0, v187
	s_waitcnt lgkmcnt(1)
	v_mfma_f32_32x32x16_bf16 v[80:95], v[216:219], v[220:223], v[80:95]
	ds_read_b128 v[216:219], v159 offset:16384
	ds_read_b128 v[220:223], v159 offset:24576
	v_add_u32_e32 v159, 0, v188
	s_waitcnt lgkmcnt(1)
	v_mfma_f32_32x32x16_bf16 v[64:79], v[216:219], v[224:227], v[64:79]
	ds_read_b128 v[216:219], v159 offset:16384
	s_waitcnt lgkmcnt(1)
	v_mfma_f32_32x32x16_bf16 v[80:95], v[220:223], v[224:227], v[80:95]
	ds_read_b128 v[220:223], v215
	s_waitcnt lgkmcnt(0)
	v_mfma_f32_32x32x16_bf16 v[64:79], v[216:219], v[220:223], v[64:79]
	ds_read_b128 v[216:219], v159 offset:24576
	v_add_u32_e32 v159, s24, v189
	ds_read_b128 v[224:227], v159
	v_add_u32_e32 v159, 0, v189
	s_waitcnt lgkmcnt(1)
	v_mfma_f32_32x32x16_bf16 v[80:95], v[216:219], v[220:223], v[80:95]
	ds_read_b128 v[216:219], v159 offset:16384
	ds_read_b128 v[220:223], v159 offset:24576
	s_waitcnt lgkmcnt(1)
	v_mfma_f32_32x32x16_bf16 v[64:79], v[216:219], v[224:227], v[64:79]
	s_waitcnt lgkmcnt(0)
	v_mfma_f32_32x32x16_bf16 v[80:95], v[220:223], v[224:227], v[80:95]
	s_cbranch_scc1 .LBB0_763
	v_add_u32_e32 v159, s14, v201
	v_add_u32_e32 v216, 0x60, v159
	v_add_u32_e32 v215, 64, v159
	v_cmp_le_i32_e32 vcc, v216, v198
	s_nop 6
	v_cndmask_b32_e32 v80, v213, v80, vcc
	v_cmp_lt_i32_e32 vcc, v215, v198
	s_nop 1
	v_cndmask_b32_e32 v65, v213, v65, vcc
	v_cmp_le_i32_e32 vcc, v215, v198
	v_add_u32_e32 v215, 0x61, v159
	s_nop 0
	v_cndmask_b32_e32 v64, v213, v64, vcc
	v_cmp_le_i32_e32 vcc, v215, v198
	v_add_u32_e32 v215, 0x42, v159
	s_nop 0
	v_cndmask_b32_e32 v81, v213, v81, vcc
	v_cmp_le_i32_e32 vcc, v215, v198
	v_add_u32_e32 v215, 0x62, v159
	s_nop 0
	v_cndmask_b32_e32 v66, v213, v66, vcc
	v_cmp_le_i32_e32 vcc, v215, v198
	v_add_u32_e32 v215, 0x43, v159
	s_nop 0
	v_cndmask_b32_e32 v82, v213, v82, vcc
	v_cmp_le_i32_e32 vcc, v215, v198
	v_add_u32_e32 v215, 0x63, v159
	s_nop 0
	v_cndmask_b32_e32 v67, v213, v67, vcc
	v_cmp_le_i32_e32 vcc, v215, v198
	v_add_u32_e32 v215, 0x48, v159
	s_nop 0
	v_cndmask_b32_e32 v83, v213, v83, vcc
	v_cmp_le_i32_e32 vcc, v215, v198
	v_add_u32_e32 v215, 0x68, v159
	s_nop 0
	v_cndmask_b32_e32 v68, v213, v68, vcc
	v_cmp_le_i32_e32 vcc, v215, v198
	v_add_u32_e32 v215, 0x49, v159
	s_nop 0
	v_cndmask_b32_e32 v84, v213, v84, vcc
	v_cmp_le_i32_e32 vcc, v215, v198
	v_add_u32_e32 v215, 0x69, v159
	s_nop 0
	v_cndmask_b32_e32 v69, v213, v69, vcc
	v_cmp_le_i32_e32 vcc, v215, v198
	v_add_u32_e32 v215, 0x4a, v159
	s_nop 0
	v_cndmask_b32_e32 v85, v213, v85, vcc
	v_cmp_le_i32_e32 vcc, v215, v198
	v_add_u32_e32 v215, 0x6a, v159
	s_nop 0
	v_cndmask_b32_e32 v70, v213, v70, vcc
	v_cmp_le_i32_e32 vcc, v215, v198
	v_add_u32_e32 v215, 0x4b, v159
	s_nop 0
	v_cndmask_b32_e32 v86, v213, v86, vcc
	v_cmp_le_i32_e32 vcc, v215, v198
	v_add_u32_e32 v215, 0x6b, v159
	s_nop 0
	v_cndmask_b32_e32 v71, v213, v71, vcc
	v_cmp_le_i32_e32 vcc, v215, v198
	v_add_u32_e32 v215, 0x50, v159
	s_nop 0
	v_cndmask_b32_e32 v87, v213, v87, vcc
	v_cmp_le_i32_e32 vcc, v215, v198
	v_add_u32_e32 v215, 0x70, v159
	s_nop 0
	v_cndmask_b32_e32 v72, v213, v72, vcc
	v_cmp_le_i32_e32 vcc, v215, v198
	v_add_u32_e32 v215, 0x51, v159
	s_nop 0
	v_cndmask_b32_e32 v88, v213, v88, vcc
	v_cmp_le_i32_e32 vcc, v215, v198
	v_add_u32_e32 v215, 0x71, v159
	s_nop 0
	v_cndmask_b32_e32 v73, v213, v73, vcc
	v_cmp_le_i32_e32 vcc, v215, v198
	v_add_u32_e32 v215, 0x52, v159
	s_nop 0
	v_cndmask_b32_e32 v89, v213, v89, vcc
	v_cmp_le_i32_e32 vcc, v215, v198
	v_add_u32_e32 v215, 0x72, v159
	s_nop 0
	v_cndmask_b32_e32 v74, v213, v74, vcc
	v_cmp_le_i32_e32 vcc, v215, v198
	v_add_u32_e32 v215, 0x53, v159
	s_nop 0
	v_cndmask_b32_e32 v90, v213, v90, vcc
	v_cmp_le_i32_e32 vcc, v215, v198
	v_add_u32_e32 v215, 0x73, v159
	s_nop 0
	v_cndmask_b32_e32 v75, v213, v75, vcc
	v_cmp_le_i32_e32 vcc, v215, v198
	v_add_u32_e32 v215, 0x58, v159
	s_nop 0
	v_cndmask_b32_e32 v91, v213, v91, vcc
	v_cmp_le_i32_e32 vcc, v215, v198
	v_add_u32_e32 v215, 0x78, v159
	s_nop 0
	v_cndmask_b32_e32 v76, v213, v76, vcc
	v_cmp_le_i32_e32 vcc, v215, v198
	v_add_u32_e32 v215, 0x59, v159
	s_nop 0
	v_cndmask_b32_e32 v92, v213, v92, vcc
	v_cmp_le_i32_e32 vcc, v215, v198
	v_add_u32_e32 v215, 0x79, v159
	s_nop 0
	v_cndmask_b32_e32 v77, v213, v77, vcc
	v_cmp_le_i32_e32 vcc, v215, v198
	v_add_u32_e32 v215, 0x5a, v159
	s_nop 0
	v_cndmask_b32_e32 v93, v213, v93, vcc
	v_cmp_le_i32_e32 vcc, v215, v198
	v_add_u32_e32 v215, 0x7a, v159
	s_nop 0
	v_cndmask_b32_e32 v78, v213, v78, vcc
	v_cmp_le_i32_e32 vcc, v215, v198
	v_add_u32_e32 v215, 0x5b, v159
	v_add_u32_e32 v159, 0x7b, v159
	v_cndmask_b32_e32 v94, v213, v94, vcc
	v_cmp_le_i32_e32 vcc, v215, v198
	s_nop 1
	v_cndmask_b32_e32 v79, v213, v79, vcc
	v_cmp_le_i32_e32 vcc, v159, v198
	s_nop 1
	v_cndmask_b32_e32 v95, v213, v95, vcc

; __device__ __forceinline__ int crow(int r, int hi) { return (r & 3) + 8 * (r >> 2) + 4 * hi; }
; __device__ __forceinline__ void qkt(f32x16& p0, f32x16& p1, const char* Ks, const char* Qs, int r32, int hi) {
; #pragma unroll
;     for (int d0 = 0; d0 < 8; ++d0) { const int cb = (d0 * 16 + hi * 8) * 2;
;         const bf16x8 qv = *reinterpret_cast<const bf16x8*>(Qs + KSWZ(r32, cb));
;         const bf16x8 b0 = *reinterpret_cast<const bf16x8*>(Ks + KSWZ(r32, cb));
;         const bf16x8 b1 = *reinterpret_cast<const bf16x8*>(Ks + KSWZ(32 + r32, cb));
;         p0 = __builtin_amdgcn_mfma_f32_32x32x16_bf16(b0, qv, p0, 0, 0, 0);
;         p1 = __builtin_amdgcn_mfma_f32_32x32x16_bf16(b1, qv, p1, 0, 0, 0); }
; template <int MODE, bool SAMPLE>
; __device__ __forceinline__ void attn_unit(const Params& p, char* lds, int b, int h, int qb) {
;     ...
;         if (wact && j <= jd && var < 2) {
;             const char* Kt = K_lds + buf * 16384; const int vb = vb0 + buf * 16384;
;             f32x16 p0, p1; bf16x8 pa0, pa1, pa2, pa3;
;             if (MODE == 0) {
;                 const float* bt = biasL + j * 64 + 4 * hi;
; #pragma unroll
;                 for (int g = 0; g < 4; ++g) { const f32x4 a = *(const f32x4*)(bt + 8 * g), c = *(const f32x4*)(bt + 32 + 8 * g);
; #pragma unroll
;                     for (int i = 0; i < 4; ++i) { p0[4 * g + i] = a[i]; p1[4 * g + i] = c[i]; } }
;                 qkt(p0, p1, Kt, Qs, r32, hi);
;                 if (j == jd) {
; #pragma unroll
;                     for (int r = 0; r < 16; ++r) { const int kp = j * 64 + crow(r, hi); if (kp > qpos) p0[r] = -1e30f; if (kp + 32 > qpos) p1[r] = -1e30f; } }
.LBB0_771:
	s_cmp_gt_i32 s18, s11
	s_waitcnt lgkmcnt(0)
	s_barrier
	s_cbranch_scc1 .LBB0_756
	v_readfirstlane_b32 s98, v183
	s_cmpk_ge_u32 s98, 0x100
	s_cbranch_scc1 .Lstg_5
	s_sleep 16
.Lstg_5:
	v_add_u32_e32 v64, s24, v181
	v_add_u32_e32 v84, 0, v181
	ds_read_b128 v[216:219], v64
	ds_read_b128 v[80:83], v84
	ds_read_b128 v[64:67], v199
	ds_read_b128 v[68:71], v199 offset:32
	ds_read_b128 v[72:75], v199 offset:64
	ds_read_b128 v[76:79], v199 offset:96
	ds_read_b128 v[220:223], v84 offset:8192
	v_add_u32_e32 v159, s24, v182
	v_add_u32_e32 v215, s24, v184
	s_waitcnt lgkmcnt(1)
	v_mfma_f32_32x32x16_bf16 v[64:79], v[80:83], v[216:219], v[64:79]
	ds_read_b128 v[80:83], v199 offset:128
	ds_read_b128 v[84:87], v199 offset:160
	ds_read_b128 v[88:91], v199 offset:192
	ds_read_b128 v[92:95], v199 offset:224
	ds_read_b128 v[224:227], v159
	v_add_u32_e32 v159, 0, v182
	s_cmp_lg_u32 s11, s18
	s_waitcnt lgkmcnt(1)
	v_mfma_f32_32x32x16_bf16 v[80:95], v[220:223], v[216:219], v[80:95]
	ds_read_b128 v[216:219], v159
	ds_read_b128 v[220:223], v159 offset:8192
	v_add_u32_e32 v159, 0, v184
	s_waitcnt lgkmcnt(1)
	v_mfma_f32_32x32x16_bf16 v[64:79], v[216:219], v[224:227], v[64:79]
	ds_read_b128 v[216:219], v159
	s_waitcnt lgkmcnt(1)
	v_mfma_f32_32x32x16_bf16 v[80:95], v[220:223], v[224:227], v[80:95]
	ds_read_b128 v[220:223], v215
	v_add_u32_e32 v215, s24, v186
	s_waitcnt lgkmcnt(0)
	v_mfma_f32_32x32x16_bf16 v[64:79], v[216:219], v[220:223], v[64:79]
	ds_read_b128 v[216:219], v159 offset:8192
	v_add_u32_e32 v159, s24, v185
	ds_read_b128 v[224:227], v159
	v_add_u32_e32 v159, 0, v185
	s_waitcnt lgkmcnt(1)
	v_mfma_f32_32x32x16_bf16 v[80:95], v[216:219], v[220:223], v[80:95]
	ds_read_b128 v[216:219], v159
	ds_read_b128 v[220:223], v159 offset:8192
	v_add_u32_e32 v159, 0, v186
	s_waitcnt lgkmcnt(1)
	v_mfma_f32_32x32x16_bf16 v[64:79], v[216:219], v[224:227], v[64:79]
	ds_read_b128 v[216:219], v159
	s_waitcnt lgkmcnt(1)
	v_mfma_f32_32x32x16_bf16 v[80:95], v[220:223], v[224:227], v[80:95]
	ds_read_b128 v[220:223], v215
	v_add_u32_e32 v215, s24, v188
	s_waitcnt lgkmcnt(0)
	v_mfma_f32_32x32x16_bf16 v[64:79], v[216:219], v[220:223], v[64:79]
	ds_read_b128 v[216:219], v159 offset:8192
	v_add_u32_e32 v159, s24, v187
	ds_read_b128 v[224:227], v159
	v_add_u32_e32 v159, 0, v187
	s_waitcnt lgkmcnt(1)
	v_mfma_f32_32x32x16_bf16 v[80:95], v[216:219], v[220:223], v[80:95]
	ds_read_b128 v[216:219], v159
	ds_read_b128 v[220:223], v159 offset:8192
	v_add_u32_e32 v159, 0, v188
	s_waitcnt lgkmcnt(1)
	v_mfma_f32_32x32x16_bf16 v[64:79], v[216:219], v[224:227], v[64:79]
	ds_read_b128 v[216:219], v159
	s_waitcnt lgkmcnt(1)
	v_mfma_f32_32x32x16_bf16 v[80:95], v[220:223], v[224:227], v[80:95]
	ds_read_b128 v[220:223], v215
	s_waitcnt lgkmcnt(0)
	v_mfma_f32_32x32x16_bf16 v[64:79], v[216:219], v[220:223], v[64:79]
	ds_read_b128 v[216:219], v159 offset:8192
	v_add_u32_e32 v159, s24, v189
	ds_read_b128 v[224:227], v159
	v_add_u32_e32 v159, 0, v189
	s_waitcnt lgkmcnt(1)
	v_mfma_f32_32x32x16_bf16 v[80:95], v[216:219], v[220:223], v[80:95]
	ds_read_b128 v[216:219], v159
	ds_read_b128 v[220:223], v159 offset:8192
	s_waitcnt lgkmcnt(1)
	v_mfma_f32_32x32x16_bf16 v[64:79], v[216:219], v[224:227], v[64:79]
	s_waitcnt lgkmcnt(0)
	v_mfma_f32_32x32x16_bf16 v[80:95], v[220:223], v[224:227], v[80:95]
	s_cbranch_scc1 .LBB0_774
	v_add_u32_e32 v159, s14, v201
	v_add_u32_e32 v215, 32, v159
	v_cmp_le_i32_e32 vcc, v215, v198
	v_add_u32_e32 v215, 33, v159
	s_nop 6
	v_cndmask_b32_e32 v80, v213, v80, vcc
	v_cmp_lt_i32_e32 vcc, v159, v198
	s_nop 1
	v_cndmask_b32_e32 v65, v213, v65, vcc
	v_cmp_le_i32_e32 vcc, v159, v198
	s_nop 1
	v_cndmask_b32_e32 v64, v213, v64, vcc
	v_cmp_le_i32_e32 vcc, v215, v198
	v_add_u32_e32 v215, 2, v159
	s_nop 0
	v_cndmask_b32_e32 v81, v213, v81, vcc
	v_cmp_le_i32_e32 vcc, v215, v198
	v_add_u32_e32 v215, 34, v159
	s_nop 0
	v_cndmask_b32_e32 v66, v213, v66, vcc
	v_cmp_le_i32_e32 vcc, v215, v198
	v_add_u32_e32 v215, 3, v159
	s_nop 0
	v_cndmask_b32_e32 v82, v213, v82, vcc
	v_cmp_le_i32_e32 vcc, v215, v198
	v_add_u32_e32 v215, 35, v159
	s_nop 0
	v_cndmask_b32_e32 v67, v213, v67, vcc
	v_cmp_le_i32_e32 vcc, v215, v198
	v_add_u32_e32 v215, 8, v159
	s_nop 0
	v_cndmask_b32_e32 v83, v213, v83, vcc
	v_cmp_le_i32_e32 vcc, v215, v198
	v_add_u32_e32 v215, 40, v159
	s_nop 0
	v_cndmask_b32_e32 v68, v213, v68, vcc
	v_cmp_le_i32_e32 vcc, v215, v198
	v_add_u32_e32 v215, 9, v159
	s_nop 0
	v_cndmask_b32_e32 v84, v213, v84, vcc
	v_cmp_le_i32_e32 vcc, v215, v198
	v_add_u32_e32 v215, 41, v159
	s_nop 0
	v_cndmask_b32_e32 v69, v213, v69, vcc
	v_cmp_le_i32_e32 vcc, v215, v198
	v_add_u32_e32 v215, 10, v159
	s_nop 0
	v_cndmask_b32_e32 v85, v213, v85, vcc
	v_cmp_le_i32_e32 vcc, v215, v198
	v_add_u32_e32 v215, 42, v159
	s_nop 0
	v_cndmask_b32_e32 v70, v213, v70, vcc
	v_cmp_le_i32_e32 vcc, v215, v198
	v_add_u32_e32 v215, 11, v159
	s_nop 0
	v_cndmask_b32_e32 v86, v213, v86, vcc
	v_cmp_le_i32_e32 vcc, v215, v198
	v_add_u32_e32 v215, 43, v159
	s_nop 0
	v_cndmask_b32_e32 v71, v213, v71, vcc
	v_cmp_le_i32_e32 vcc, v215, v198
	v_add_u32_e32 v215, 16, v159
	s_nop 0
	v_cndmask_b32_e32 v87, v213, v87, vcc
	v_cmp_le_i32_e32 vcc, v215, v198
	v_add_u32_e32 v215, 48, v159
	s_nop 0
	v_cndmask_b32_e32 v72, v213, v72, vcc
	v_cmp_le_i32_e32 vcc, v215, v198
	v_add_u32_e32 v215, 17, v159
	s_nop 0
	v_cndmask_b32_e32 v88, v213, v88, vcc
	v_cmp_le_i32_e32 vcc, v215, v198
	v_add_u32_e32 v215, 49, v159
	s_nop 0
	v_cndmask_b32_e32 v73, v213, v73, vcc
	v_cmp_le_i32_e32 vcc, v215, v198
	v_add_u32_e32 v215, 18, v159
	s_nop 0
	v_cndmask_b32_e32 v89, v213, v89, vcc
	v_cmp_le_i32_e32 vcc, v215, v198
	v_add_u32_e32 v215, 50, v159
	s_nop 0
	v_cndmask_b32_e32 v74, v213, v74, vcc
	v_cmp_le_i32_e32 vcc, v215, v198
	v_add_u32_e32 v215, 19, v159
	s_nop 0
	v_cndmask_b32_e32 v90, v213, v90, vcc
	v_cmp_le_i32_e32 vcc, v215, v198
	v_add_u32_e32 v215, 51, v159
	s_nop 0
	v_cndmask_b32_e32 v75, v213, v75, vcc
	v_cmp_le_i32_e32 vcc, v215, v198
	v_add_u32_e32 v215, 24, v159
	s_nop 0
	v_cndmask_b32_e32 v91, v213, v91, vcc
	v_cmp_le_i32_e32 vcc, v215, v198
	v_add_u32_e32 v215, 56, v159
	s_nop 0
	v_cndmask_b32_e32 v76, v213, v76, vcc
	v_cmp_le_i32_e32 vcc, v215, v198
	v_add_u32_e32 v215, 25, v159
	s_nop 0
	v_cndmask_b32_e32 v92, v213, v92, vcc
	v_cmp_le_i32_e32 vcc, v215, v198
	v_add_u32_e32 v215, 57, v159
	s_nop 0
	v_cndmask_b32_e32 v77, v213, v77, vcc
	v_cmp_le_i32_e32 vcc, v215, v198
	v_add_u32_e32 v215, 26, v159
	s_nop 0
	v_cndmask_b32_e32 v93, v213, v93, vcc
	v_cmp_le_i32_e32 vcc, v215, v198
	v_add_u32_e32 v215, 58, v159
	s_nop 0
	v_cndmask_b32_e32 v78, v213, v78, vcc
	v_cmp_le_i32_e32 vcc, v215, v198
	v_add_u32_e32 v215, 27, v159
	v_add_u32_e32 v159, 59, v159
	v_cndmask_b32_e32 v94, v213, v94, vcc
	v_cmp_le_i32_e32 vcc, v215, v198
	s_nop 1
	v_cndmask_b32_e32 v79, v213, v79, vcc
	v_cmp_le_i32_e32 vcc, v159, v198
	s_nop 1
	v_cndmask_b32_e32 v95, v213, v95, vcc

; __device__ __forceinline__ int crow(int r, int hi) { return (r & 3) + 8 * (r >> 2) + 4 * hi; }
; __device__ __forceinline__ void qkt(f32x16& p0, f32x16& p1, const char* Ks, const char* Qs, int r32, int hi) {
; #pragma unroll
;     for (int d0 = 0; d0 < 8; ++d0) { const int cb = (d0 * 16 + hi * 8) * 2;
;         const bf16x8 qv = *reinterpret_cast<const bf16x8*>(Qs + KSWZ(r32, cb));
;         const bf16x8 b0 = *reinterpret_cast<const bf16x8*>(Ks + KSWZ(r32, cb));
;         const bf16x8 b1 = *reinterpret_cast<const bf16x8*>(Ks + KSWZ(32 + r32, cb));
;         p0 = __builtin_amdgcn_mfma_f32_32x32x16_bf16(b0, qv, p0, 0, 0, 0);
;         p1 = __builtin_amdgcn_mfma_f32_32x32x16_bf16(b1, qv, p1, 0, 0, 0); }
; template <int MODE, bool SAMPLE>
; __device__ __forceinline__ void attn_unit(const Params& p, char* lds, int b, int h, int qb) {
;     ...
;             } else {
;                 p0 = f32x16{}; p1 = f32x16{};
;                 qkt(p0, p1, Kt, Qs, r32, hi);
;                 if (j == jd) {
; #pragma unroll
;                     for (int r = 0; r < 16; ++r) { const int kp = j * 64 + crow(r, hi); if (kp >= qpos) p0[r] = -1e30f; if (kp + 32 >= qpos) p1[r] = -1e30f; } }
.LBB0_786:
	s_cmp_ge_u32 s33, s11
	s_waitcnt lgkmcnt(0)
	s_barrier
	s_cbranch_scc1 .LBB0_790
	v_readfirstlane_b32 s98, v183
	s_cmpk_ge_u32 s98, 0x100
	s_cbranch_scc1 .Lstg_6
	s_sleep 16
.Lstg_6:
	v_add_u32_e32 v72, 0, v181
	ds_read_b128 v[64:67], v72 offset:16384
	v_add_u32_e32 v68, s10, v181
	ds_read_b128 v[68:71], v68
	v_add_u32_e32 v149, 0, v182
	v_add_u32_e32 v159, s10, v182
	ds_read_b128 v[218:221], v159
	v_add_u32_e32 v159, s10, v184
	s_cmp_lg_u32 s97, s33
	s_waitcnt lgkmcnt(1)
	v_mfma_f32_32x32x16_bf16 v[80:95], v[64:67], v[68:71], 0
	ds_read_b128 v[64:67], v72 offset:24576
	ds_read_b128 v[214:217], v149 offset:16384
	s_waitcnt lgkmcnt(0)
	v_mfma_f32_32x32x16_bf16 v[80:95], v[214:217], v[218:221], v[80:95]
	ds_read_b128 v[214:217], v149 offset:24576
	v_add_u32_e32 v149, 0, v184
	v_mfma_f32_32x32x16_bf16 v[64:79], v[64:67], v[68:71], 0
	s_waitcnt lgkmcnt(0)
	v_mfma_f32_32x32x16_bf16 v[64:79], v[214:217], v[218:221], v[64:79]
	ds_read_b128 v[214:217], v149 offset:16384
	ds_read_b128 v[218:221], v159
	v_add_u32_e32 v159, s10, v185
	s_waitcnt lgkmcnt(0)
	v_mfma_f32_32x32x16_bf16 v[80:95], v[214:217], v[218:221], v[80:95]
	ds_read_b128 v[214:217], v149 offset:24576
	v_add_u32_e32 v149, 0, v185
	s_waitcnt lgkmcnt(0)
	v_mfma_f32_32x32x16_bf16 v[64:79], v[214:217], v[218:221], v[64:79]
	ds_read_b128 v[214:217], v149 offset:16384
	ds_read_b128 v[218:221], v159
	v_add_u32_e32 v159, s10, v186
	s_waitcnt lgkmcnt(0)
	v_mfma_f32_32x32x16_bf16 v[80:95], v[214:217], v[218:221], v[80:95]
	ds_read_b128 v[214:217], v149 offset:24576
	v_add_u32_e32 v149, 0, v186
	s_waitcnt lgkmcnt(0)
	v_mfma_f32_32x32x16_bf16 v[64:79], v[214:217], v[218:221], v[64:79]
	ds_read_b128 v[214:217], v149 offset:16384
	ds_read_b128 v[218:221], v159
	v_add_u32_e32 v159, s10, v187
	s_waitcnt lgkmcnt(0)
	v_mfma_f32_32x32x16_bf16 v[80:95], v[214:217], v[218:221], v[80:95]
	ds_read_b128 v[214:217], v149 offset:24576
	v_add_u32_e32 v149, 0, v187
	s_waitcnt lgkmcnt(0)
	v_mfma_f32_32x32x16_bf16 v[64:79], v[214:217], v[218:221], v[64:79]
	ds_read_b128 v[214:217], v149 offset:16384
	ds_read_b128 v[218:221], v159
	v_add_u32_e32 v159, s10, v188
	s_waitcnt lgkmcnt(0)
	v_mfma_f32_32x32x16_bf16 v[80:95], v[214:217], v[218:221], v[80:95]
	ds_read_b128 v[214:217], v149 offset:24576
	v_add_u32_e32 v149, 0, v188
	s_waitcnt lgkmcnt(0)
	v_mfma_f32_32x32x16_bf16 v[64:79], v[214:217], v[218:221], v[64:79]
	ds_read_b128 v[214:217], v149 offset:16384
	ds_read_b128 v[218:221], v159
	v_add_u32_e32 v159, s10, v189
	s_waitcnt lgkmcnt(0)
	v_mfma_f32_32x32x16_bf16 v[80:95], v[214:217], v[218:221], v[80:95]
	ds_read_b128 v[214:217], v149 offset:24576
	v_add_u32_e32 v149, 0, v189
	s_waitcnt lgkmcnt(0)
	v_mfma_f32_32x32x16_bf16 v[64:79], v[214:217], v[218:221], v[64:79]
	ds_read_b128 v[214:217], v149 offset:16384
	ds_read_b128 v[218:221], v159
	s_waitcnt lgkmcnt(0)
	v_mfma_f32_32x32x16_bf16 v[80:95], v[214:217], v[218:221], v[80:95]
	ds_read_b128 v[214:217], v149 offset:24576
	s_waitcnt lgkmcnt(0)
	v_mfma_f32_32x32x16_bf16 v[64:79], v[214:217], v[218:221], v[64:79]
	s_cbranch_scc1 .LBB0_789
	s_or_b64 s[78:79], s[74:75], s[70:71]
	s_nop 6
	v_cndmask_b32_e64 v94, v213, v94, s[78:79]
	s_or_b64 s[78:79], s[78:79], s[66:67]
	v_cndmask_b32_e64 v93, v213, v93, s[78:79]
	s_or_b64 s[78:79], s[78:79], s[62:63]
	v_cndmask_b32_e64 v92, v213, v92, s[78:79]
	s_or_b64 s[78:79], s[78:79], s[58:59]
	v_cndmask_b32_e64 v91, v213, v91, s[78:79]
	s_or_b64 s[78:79], s[78:79], s[54:55]
	v_cndmask_b32_e64 v90, v213, v90, s[78:79]
	s_or_b64 s[78:79], s[78:79], s[50:51]
	v_cndmask_b32_e64 v89, v213, v89, s[78:79]
	s_or_b64 s[78:79], s[78:79], s[46:47]
	v_cndmask_b32_e64 v88, v213, v88, s[78:79]
	s_or_b64 s[78:79], s[78:79], s[42:43]
	v_cndmask_b32_e64 v87, v213, v87, s[78:79]
	s_or_b64 s[78:79], s[78:79], s[38:39]
	v_cndmask_b32_e64 v86, v213, v86, s[78:79]
	s_or_b64 s[78:79], s[78:79], s[34:35]
	v_cndmask_b32_e64 v85, v213, v85, s[78:79]
	s_or_b64 s[78:79], s[78:79], s[28:29]
	v_cndmask_b32_e64 v84, v213, v84, s[78:79]
	s_or_b64 s[78:79], s[78:79], s[24:25]
	v_cndmask_b32_e64 v83, v213, v83, s[78:79]
	s_or_b64 s[78:79], s[78:79], s[20:21]
	v_cndmask_b32_e64 v82, v213, v82, s[78:79]
	s_or_b64 s[78:79], s[78:79], s[16:17]
	v_cndmask_b32_e64 v81, v213, v81, s[78:79]
	s_or_b64 s[78:79], s[78:79], vcc
	v_cndmask_b32_e64 v80, v213, v80, s[78:79]
	s_or_b64 s[78:79], s[76:77], s[72:73]
	v_cndmask_b32_e64 v78, v213, v78, s[78:79]
	s_or_b64 s[78:79], s[78:79], s[68:69]
	v_cndmask_b32_e64 v77, v213, v77, s[78:79]
	s_or_b64 s[78:79], s[78:79], s[64:65]
	v_cndmask_b32_e64 v76, v213, v76, s[78:79]
	s_or_b64 s[78:79], s[78:79], s[60:61]
	v_cndmask_b32_e64 v75, v213, v75, s[78:79]
	s_or_b64 s[78:79], s[78:79], s[56:57]
	v_cndmask_b32_e64 v74, v213, v74, s[78:79]
	s_or_b64 s[78:79], s[78:79], s[52:53]
	v_cndmask_b32_e64 v73, v213, v73, s[78:79]
	s_or_b64 s[78:79], s[78:79], s[48:49]
	v_cndmask_b32_e64 v72, v213, v72, s[78:79]
	s_or_b64 s[78:79], s[78:79], s[44:45]
	v_cndmask_b32_e64 v71, v213, v71, s[78:79]
	s_or_b64 s[78:79], s[78:79], s[40:41]
	v_cndmask_b32_e64 v70, v213, v70, s[78:79]
	s_or_b64 s[78:79], s[78:79], s[36:37]
	v_cndmask_b32_e64 v69, v213, v69, s[78:79]
	s_or_b64 s[78:79], s[78:79], s[30:31]
	v_cndmask_b32_e64 v68, v213, v68, s[78:79]
	s_or_b64 s[78:79], s[78:79], s[26:27]
	v_cndmask_b32_e64 v67, v213, v67, s[78:79]
	s_or_b64 s[78:79], s[78:79], s[22:23]
	v_cndmask_b32_e64 v66, v213, v66, s[78:79]
	s_or_b64 s[78:79], s[78:79], s[18:19]
	v_cndmask_b32_e64 v65, v213, v65, s[78:79]
	s_or_b64 s[78:79], s[78:79], s[0:1]
	v_cndmask_b32_e64 v95, v213, v95, s[74:75]
	v_cndmask_b32_e64 v79, v213, v79, s[76:77]
	v_cndmask_b32_e64 v64, v213, v64, s[78:79]

; __device__ __forceinline__ int crow(int r, int hi) { return (r & 3) + 8 * (r >> 2) + 4 * hi; }
; __device__ __forceinline__ void qkt(f32x16& p0, f32x16& p1, const char* Ks, const char* Qs, int r32, int hi) {
; #pragma unroll
;     for (int d0 = 0; d0 < 8; ++d0) { const int cb = (d0 * 16 + hi * 8) * 2;
;         const bf16x8 qv = *reinterpret_cast<const bf16x8*>(Qs + KSWZ(r32, cb));
;         const bf16x8 b0 = *reinterpret_cast<const bf16x8*>(Ks + KSWZ(r32, cb));
;         const bf16x8 b1 = *reinterpret_cast<const bf16x8*>(Ks + KSWZ(32 + r32, cb));
;         p0 = __builtin_amdgcn_mfma_f32_32x32x16_bf16(b0, qv, p0, 0, 0, 0);
;         p1 = __builtin_amdgcn_mfma_f32_32x32x16_bf16(b1, qv, p1, 0, 0, 0); }
; template <int MODE, bool SAMPLE>
; __device__ __forceinline__ void attn_unit(const Params& p, char* lds, int b, int h, int qb) {
;     ...
;             } else {
;                 p0 = f32x16{}; p1 = f32x16{};
;                 qkt(p0, p1, Kt, Qs, r32, hi);
;                 if (j == jd) {
; #pragma unroll
;                     for (int r = 0; r < 16; ++r) { const int kp = j * 64 + crow(r, hi); if (kp >= qpos) p0[r] = -1e30f; if (kp + 32 >= qpos) p1[r] = -1e30f; } }
.LBB0_793:
	s_cmp_gt_u32 s33, s11
	s_waitcnt lgkmcnt(0)
	s_barrier
	s_cbranch_scc1 .LBB0_782
	v_readfirstlane_b32 s98, v183
	s_cmpk_ge_u32 s98, 0x100
	s_cbranch_scc1 .Lstg_7
	s_sleep 16
.Lstg_7:
	v_add_u32_e32 v72, 0, v181
	ds_read_b128 v[64:67], v72
	v_add_u32_e32 v68, s10, v181
	ds_read_b128 v[68:71], v68
	v_add_u32_e32 v149, 0, v182
	v_add_u32_e32 v159, s10, v182
	ds_read_b128 v[218:221], v159
	v_add_u32_e32 v159, s10, v184
	s_cmp_lg_u32 s11, s33
	s_waitcnt lgkmcnt(1)
	v_mfma_f32_32x32x16_bf16 v[80:95], v[64:67], v[68:71], 0
	ds_read_b128 v[64:67], v72 offset:8192
	ds_read_b128 v[214:217], v149
	s_waitcnt lgkmcnt(0)
	v_mfma_f32_32x32x16_bf16 v[80:95], v[214:217], v[218:221], v[80:95]
	ds_read_b128 v[214:217], v149 offset:8192
	v_add_u32_e32 v149, 0, v184
	v_mfma_f32_32x32x16_bf16 v[64:79], v[64:67], v[68:71], 0
	s_waitcnt lgkmcnt(0)
	v_mfma_f32_32x32x16_bf16 v[64:79], v[214:217], v[218:221], v[64:79]
	ds_read_b128 v[214:217], v149
	ds_read_b128 v[218:221], v159
	v_add_u32_e32 v159, s10, v185
	s_waitcnt lgkmcnt(0)
	v_mfma_f32_32x32x16_bf16 v[80:95], v[214:217], v[218:221], v[80:95]
	ds_read_b128 v[214:217], v149 offset:8192
	v_add_u32_e32 v149, 0, v185
	s_waitcnt lgkmcnt(0)
	v_mfma_f32_32x32x16_bf16 v[64:79], v[214:217], v[218:221], v[64:79]
	ds_read_b128 v[214:217], v149
	ds_read_b128 v[218:221], v159
	v_add_u32_e32 v159, s10, v186
	s_waitcnt lgkmcnt(0)
	v_mfma_f32_32x32x16_bf16 v[80:95], v[214:217], v[218:221], v[80:95]
	ds_read_b128 v[214:217], v149 offset:8192
	v_add_u32_e32 v149, 0, v186
	s_waitcnt lgkmcnt(0)
	v_mfma_f32_32x32x16_bf16 v[64:79], v[214:217], v[218:221], v[64:79]
	ds_read_b128 v[214:217], v149
	ds_read_b128 v[218:221], v159
	v_add_u32_e32 v159, s10, v187
	s_waitcnt lgkmcnt(0)
	v_mfma_f32_32x32x16_bf16 v[80:95], v[214:217], v[218:221], v[80:95]
	ds_read_b128 v[214:217], v149 offset:8192
	v_add_u32_e32 v149, 0, v187
	s_waitcnt lgkmcnt(0)
	v_mfma_f32_32x32x16_bf16 v[64:79], v[214:217], v[218:221], v[64:79]
	ds_read_b128 v[214:217], v149
	ds_read_b128 v[218:221], v159
	v_add_u32_e32 v159, s10, v188
	s_waitcnt lgkmcnt(0)
	v_mfma_f32_32x32x16_bf16 v[80:95], v[214:217], v[218:221], v[80:95]
	ds_read_b128 v[214:217], v149 offset:8192
	v_add_u32_e32 v149, 0, v188
	s_waitcnt lgkmcnt(0)
	v_mfma_f32_32x32x16_bf16 v[64:79], v[214:217], v[218:221], v[64:79]
	ds_read_b128 v[214:217], v149
	ds_read_b128 v[218:221], v159
	v_add_u32_e32 v159, s10, v189
	s_waitcnt lgkmcnt(0)
	v_mfma_f32_32x32x16_bf16 v[80:95], v[214:217], v[218:221], v[80:95]
	ds_read_b128 v[214:217], v149 offset:8192
	v_add_u32_e32 v149, 0, v189
	s_waitcnt lgkmcnt(0)
	v_mfma_f32_32x32x16_bf16 v[64:79], v[214:217], v[218:221], v[64:79]
	ds_read_b128 v[214:217], v149
	ds_read_b128 v[218:221], v159
	s_waitcnt lgkmcnt(0)
	v_mfma_f32_32x32x16_bf16 v[80:95], v[214:217], v[218:221], v[80:95]
	ds_read_b128 v[214:217], v149 offset:8192
	s_waitcnt lgkmcnt(0)
	v_mfma_f32_32x32x16_bf16 v[64:79], v[214:217], v[218:221], v[64:79]
	s_cbranch_scc1 .LBB0_781
	s_or_b64 s[78:79], s[74:75], s[70:71]
	s_nop 6
	v_cndmask_b32_e64 v94, v213, v94, s[78:79]
	s_or_b64 s[78:79], s[78:79], s[66:67]
	v_cndmask_b32_e64 v93, v213, v93, s[78:79]
	s_or_b64 s[78:79], s[78:79], s[62:63]
	v_cndmask_b32_e64 v92, v213, v92, s[78:79]
	s_or_b64 s[78:79], s[78:79], s[58:59]
	v_cndmask_b32_e64 v91, v213, v91, s[78:79]
	s_or_b64 s[78:79], s[78:79], s[54:55]
	v_cndmask_b32_e64 v90, v213, v90, s[78:79]
	s_or_b64 s[78:79], s[78:79], s[50:51]
	v_cndmask_b32_e64 v89, v213, v89, s[78:79]
	s_or_b64 s[78:79], s[78:79], s[46:47]
	v_cndmask_b32_e64 v88, v213, v88, s[78:79]
	s_or_b64 s[78:79], s[78:79], s[42:43]
	v_cndmask_b32_e64 v87, v213, v87, s[78:79]
	s_or_b64 s[78:79], s[78:79], s[38:39]
	v_cndmask_b32_e64 v86, v213, v86, s[78:79]
	s_or_b64 s[78:79], s[78:79], s[34:35]
	v_cndmask_b32_e64 v85, v213, v85, s[78:79]
	s_or_b64 s[78:79], s[78:79], s[28:29]
	v_cndmask_b32_e64 v84, v213, v84, s[78:79]
	s_or_b64 s[78:79], s[78:79], s[24:25]
	v_cndmask_b32_e64 v83, v213, v83, s[78:79]
	s_or_b64 s[78:79], s[78:79], s[20:21]
	v_cndmask_b32_e64 v82, v213, v82, s[78:79]
	s_or_b64 s[78:79], s[78:79], s[16:17]
	v_cndmask_b32_e64 v81, v213, v81, s[78:79]
	s_or_b64 s[78:79], s[78:79], vcc
	v_cndmask_b32_e64 v80, v213, v80, s[78:79]
	s_or_b64 s[78:79], s[76:77], s[72:73]
	v_cndmask_b32_e64 v78, v213, v78, s[78:79]
	s_or_b64 s[78:79], s[78:79], s[68:69]
	v_cndmask_b32_e64 v77, v213, v77, s[78:79]
	s_or_b64 s[78:79], s[78:79], s[64:65]
	v_cndmask_b32_e64 v76, v213, v76, s[78:79]
	s_or_b64 s[78:79], s[78:79], s[60:61]
	v_cndmask_b32_e64 v75, v213, v75, s[78:79]
	s_or_b64 s[78:79], s[78:79], s[56:57]
	v_cndmask_b32_e64 v74, v213, v74, s[78:79]
	s_or_b64 s[78:79], s[78:79], s[52:53]
	v_cndmask_b32_e64 v73, v213, v73, s[78:79]
	s_or_b64 s[78:79], s[78:79], s[48:49]
	v_cndmask_b32_e64 v72, v213, v72, s[78:79]
	s_or_b64 s[78:79], s[78:79], s[44:45]
	v_cndmask_b32_e64 v71, v213, v71, s[78:79]
	s_or_b64 s[78:79], s[78:79], s[40:41]
	v_cndmask_b32_e64 v70, v213, v70, s[78:79]
	s_or_b64 s[78:79], s[78:79], s[36:37]
	v_cndmask_b32_e64 v69, v213, v69, s[78:79]
	s_or_b64 s[78:79], s[78:79], s[30:31]
	v_cndmask_b32_e64 v68, v213, v68, s[78:79]
	s_or_b64 s[78:79], s[78:79], s[26:27]
	v_cndmask_b32_e64 v67, v213, v67, s[78:79]
	s_or_b64 s[78:79], s[78:79], s[22:23]
	v_cndmask_b32_e64 v66, v213, v66, s[78:79]
	s_or_b64 s[78:79], s[78:79], s[18:19]
	v_cndmask_b32_e64 v65, v213, v65, s[78:79]
	s_or_b64 s[78:79], s[78:79], s[0:1]
	v_cndmask_b32_e64 v95, v213, v95, s[74:75]
	v_cndmask_b32_e64 v79, v213, v79, s[76:77]
	v_cndmask_b32_e64 v64, v213, v64, s[78:79]
	s_branch .LBB0_781

; __device__ __forceinline__ int crow(int r, int hi) { return (r & 3) + 8 * (r >> 2) + 4 * hi; }
; __device__ __forceinline__ bf16x8 tobf8(f32x8 x) { u32x4 w = {cvtpk(x[0], x[1]), cvtpk(x[2], x[3]), cvtpk(x[4], x[5]), cvtpk(x[6], x[7])}; return *reinterpret_cast<bf16x8*>(&w); }
; __device__ __forceinline__ void spatial_phase(const Params& p, char* lds) {
;     ...
;         SP_DECODE(u, samp, g, cidx, rbase, nrows)
;         const bool act = samp ? (tb == 0) : true; const int nit = samp ? 4 : 8;
;         if (g != g_loaded) { g_loaded = g;
; #pragma unroll
;             for (int st_ = 0; st_ < 2; ++st_)
; #pragma unroll
;                 for (int ks = 0; ks < 4; ++ks) { const int s0 = 64 * st_ + 16 * ks + 8 * hi; const float* wp = p.w_sp + ((size_t)g * CCH + t) * CCH + s0;
;                     const f32x4 a = *(const f32x4*)wp, c = *(const f32x4*)(wp + 4); f32x8 y;
; #pragma unroll
;                     for (int i = 0; i < 4; ++i) { y[i] = (s0 + i <= t) ? a[i] : 0.f; y[4 + i] = (s0 + 4 + i <= t) ? c[i] : 0.f; }
;                     pa[st_][ks] = tobf8(y); }
; #pragma unroll
;             for (int r = 0; r < 16; ++r) bsp_[r] = p.b_sp[g * CCH + 32 * tb + crow(r, hi)]; }
;         bf16x8 uu[8];
;         if (act) {
; #pragma unroll
;             for (int it = 0; it < 8; ++it) if (it < nit) { const size_t row = rbase + 32 * tb + it * 4 + er; uu[it] = __builtin_nontemporal_load((const bf16x8*)(UVZ + ((size_t)g * MT + row) * 256 + ch * 128 + ec)); } }
;     ...
;                     const f32x4 g0 = *(const f32x4*)(p.ln_g + g * GD + cc), g1 = *(const f32x4*)(p.ln_g + g * GD + cc + 4), b0 = *(const f32x4*)(p.ln_b + g * GD + cc), b1 = *(const f32x4*)(p.ln_b + g * GD + cc + 4);
.LBB0_1202:
	s_lshl_b32 s74, s42, 10
	v_lshl_add_u64 v[22:23], v[220:221], 0, s[74:75]
	v_lshl_add_u64 v[24:25], v[222:223], 0, s[74:75]
	global_load_dwordx4 v[32:35], v[22:23], off
	global_load_dwordx4 v[36:39], v[22:23], off offset:16
	global_load_dwordx4 v[48:51], v[22:23], off offset:512
	global_load_dwordx4 v[52:55], v[22:23], off offset:528
	global_load_dwordx4 v[40:43], v[24:25], off
	global_load_dwordx4 v[44:47], v[24:25], off offset:16
	global_load_dwordx4 v[56:59], v[24:25], off offset:512
	global_load_dwordx4 v[60:63], v[24:25], off offset:528
	s_waitcnt vmcnt(0)
	s_cmpk_lt_i32 s79, 0x400
	s_cselect_b64 s[38:39], -1, 0
	v_cndmask_b32_e64 v0, 0, 1, s[38:39]
	s_ashr_i32 s38, s79, 4
	s_and_b32 s58, s79, -16
	s_ashr_i32 s39, s38, 31
	s_add_i32 s43, s58, 0x1c00
	s_lshl_b64 s[38:39], s[38:39], 7
	s_cmpk_gt_i32 s79, 0x3ff
	s_cselect_b64 s[68:69], -1, 0
	s_and_b64 s[40:41], s[68:69], exec
	s_cselect_b32 s67, 0, s39
	s_cselect_b32 s66, s43, s38
	s_and_b64 s[40:41], s[68:69], s[46:47]
	s_and_b64 vcc, exec, s[40:41]
	v_cmp_ne_u32_e64 s[38:39], 1, v0
	s_cbranch_vccnz .LBB0_1211
	s_mul_i32 s43, s42, 0x2200
	v_or_b32_e32 v0, s43, v207
	v_mov_b32_e32 v1, v96
	v_lshl_add_u64 v[0:1], s[66:67], 0, v[0:1]
	v_lshlrev_b64 v[2:3], 9, v[0:1]
	v_or_b32_e32 v4, 0x800, v2
	v_mov_b32_e32 v5, v3
	v_lshl_add_u64 v[0:1], v[190:191], 0, v[2:3]
	v_lshl_add_u64 v[4:5], v[190:191], 0, v[4:5]
	global_load_dwordx4 v[120:123], v[0:1], off nt
	global_load_dwordx4 v[116:119], v[4:5], off nt
	v_or_b32_e32 v4, 0x1000, v2
	v_mov_b32_e32 v5, v3
	v_lshl_add_u64 v[4:5], v[190:191], 0, v[4:5]
	v_or_b32_e32 v2, 0x1800, v2
	v_lshl_add_u64 v[2:3], v[190:191], 0, v[2:3]
	global_load_dwordx4 v[128:131], v[4:5], off nt
	global_load_dwordx4 v[124:127], v[2:3], off nt
	s_and_b64 vcc, exec, s[38:39]
	s_cbranch_vccnz .LBB0_1207
	v_add_co_u32_e32 v2, vcc, 0x2000, v0
	s_nop 1
	v_addc_co_u32_e32 v3, vcc, 0, v1, vcc
	global_load_dwordx4 v[112:115], v[2:3], off nt
	s_and_b64 vcc, exec, s[38:39]
	s_cbranch_vccz .LBB0_1208

; __device__ __forceinline__ float bf2f(short s) { return __uint_as_float(((unsigned)(unsigned short)s) << 16); }
; __device__ __forceinline__ bf16x8 tobf8(f32x8 x) { u32x4 w = {cvtpk(x[0], x[1]), cvtpk(x[2], x[3]), cvtpk(x[4], x[5]), cvtpk(x[6], x[7])}; return *reinterpret_cast<bf16x8*>(&w); }
; __device__ __forceinline__ int v_st(int k, int c) { const int kk = (k & ~0xC) | ((k & 4) << 1) | ((k & 8) >> 1); return ((kk >> 3) * 4 + (c >> 5)) * 512 + ((kk & 7) * 32 + (c & 31)) * 2; }
; __device__ __forceinline__ void spatial_phase(const Params& p, char* lds) {
;     ...
;         for (int q = 0; q < 4; ++q) { const int st_ = q >> 1, ch_ = q & 1; if (samp && st_ == 1) continue;
; #pragma unroll
;             for (int hf = 0; hf < 2; ++hf) { const int k = sr + 32 * hf, s = st_ * 64 + k; const int cc = ch_ * 128 + sc;
;                 bf16x8 w = {};
;                 if (s < nrows) { const float mu = mu_[st_ * 2 + hf], rs = rs_[st_ * 2 + hf];
;                     const bf16x8 rw = raw[q * 2 + hf];
;                     const f32x4 g0 = *(const f32x4*)(p.ln_g + g * GD + cc), g1 = *(const f32x4*)(p.ln_g + g * GD + cc + 4), b0 = *(const f32x4*)(p.ln_b + g * GD + cc), b1 = *(const f32x4*)(p.ln_b + g * GD + cc + 4);
;                     f32x8 y;
; #pragma unroll
;                     for (int i = 0; i < 4; ++i) { y[i] = (bf2f(rw[i]) - mu) * rs * g0[i] + b0[i]; y[4 + i] = (bf2f(rw[4 + i]) - mu) * rs * g1[i] + b1[i]; }
;                     if (samp) { float* d = p.out + O_SGV + (size_t)(cidx * TS + s) * CW + g * GD + cc; __builtin_nontemporal_store((f32x4){y[0], y[1], y[2], y[3]}, (f32x4*)d); __builtin_nontemporal_store((f32x4){y[4], y[5], y[6], y[7]}, (f32x4*)(d + 4)); }
;                     w = tobf8(y); }
;                 *(bf16x8*)(lds + q * 16384 + v_st(k, sc)) = w; } }
.LBB0_1211:
	s_xor_b64 s[70:71], s[40:41], -1
	s_addk_i32 s58, 0xfc00
	s_and_b64 s[40:41], s[68:69], exec
	s_cselect_b32 s59, 16, 0x80
	v_cndmask_b32_e64 v0, 0, 1, s[68:69]
	s_lshl_b32 s80, s42, 8
	v_cmp_gt_u32_e64 s[42:43], s59, v180
	v_mov_b32_e32 v3, 0
	v_cmp_ne_u32_e64 s[40:41], 1, v0
	v_mov_b32_e32 v2, 0
	v_mov_b32_e32 v1, 0
	v_mov_b32_e32 v0, 0
	s_and_saveexec_b64 s[44:45], s[42:43]
	s_cbranch_execz .LBB0_1215
	s_lshl_b32 s74, s80, 2
	v_lshl_add_u64 v[0:1], v[220:221], 0, s[74:75]
	v_lshl_add_u64 v[12:13], v[222:223], 0, s[74:75]
	s_nop 0
	s_nop 0
	s_nop 0
	v_and_b32_e32 v17, 0xffff0000, v64
	v_lshlrev_b32_e32 v16, 16, v64
	v_pk_add_f32 v[16:17], v[16:17], v[186:187] op_sel_hi:[1,0] neg_lo:[0,1] neg_hi:[0,1]
	s_and_b64 vcc, exec, s[40:41]
	v_pk_mul_f32 v[16:17], v[16:17], v[98:99] op_sel_hi:[1,0]
	v_mov_b32_e32 v4, v36
	v_mov_b32_e32 v5, v37
	v_mov_b32_e32 v6, v38
	v_mov_b32_e32 v7, v39
	v_mov_b32_e32 v0, v32
	v_mov_b32_e32 v1, v33
	v_mov_b32_e32 v2, v34
	v_mov_b32_e32 v3, v35
	v_mov_b32_e32 v8, v44
	v_mov_b32_e32 v9, v45
	v_mov_b32_e32 v10, v46
	v_mov_b32_e32 v11, v47
	v_mov_b32_e32 v12, v40
	v_mov_b32_e32 v13, v41
	v_mov_b32_e32 v14, v42
	v_mov_b32_e32 v15, v43
	v_pk_fma_f32 v[0:1], v[16:17], v[0:1], v[12:13]
	v_and_b32_e32 v13, 0xffff0000, v66
	v_lshlrev_b32_e32 v12, 16, v66
	v_pk_add_f32 v[12:13], v[12:13], v[186:187] op_sel_hi:[1,0] neg_lo:[0,1] neg_hi:[0,1]
	s_nop 0
	v_pk_mul_f32 v[12:13], v[12:13], v[98:99] op_sel_hi:[1,0]
	s_nop 0
	v_pk_fma_f32 v[4:5], v[12:13], v[4:5], v[8:9]
	v_and_b32_e32 v9, 0xffff0000, v65
	v_lshlrev_b32_e32 v8, 16, v65
	v_pk_add_f32 v[8:9], v[8:9], v[186:187] op_sel_hi:[1,0] neg_lo:[0,1] neg_hi:[0,1]
	s_nop 0
	v_pk_mul_f32 v[8:9], v[8:9], v[98:99] op_sel_hi:[1,0]
	s_nop 0
	v_pk_fma_f32 v[2:3], v[8:9], v[2:3], v[14:15]
	v_and_b32_e32 v9, 0xffff0000, v67
	v_lshlrev_b32_e32 v8, 16, v67
	v_pk_add_f32 v[8:9], v[8:9], v[186:187] op_sel_hi:[1,0] neg_lo:[0,1] neg_hi:[0,1]
	s_nop 0
	v_pk_mul_f32 v[8:9], v[8:9], v[98:99] op_sel_hi:[1,0]
	s_nop 0
	v_pk_fma_f32 v[6:7], v[8:9], v[6:7], v[10:11]
	s_cbranch_vccnz .LBB0_1214
	v_add_u32_e32 v8, s58, v180
	v_ashrrev_i32_e32 v9, 31, v8
	v_lshlrev_b64 v[8:9], 14, v[8:9]
	v_lshl_add_u64 v[8:9], s[62:63], 0, v[8:9]
	v_lshl_add_u64 v[8:9], v[8:9], 0, s[74:75]
	v_lshlrev_b32_e32 v10, 2, v182
	v_mov_b32_e32 v11, v96
	v_lshl_add_u64 v[8:9], v[8:9], 0, v[10:11]
	global_store_dwordx4 v[8:9], v[0:3], off nt
	global_store_dwordx4 v[8:9], v[4:7], off offset:16 nt

; __device__ __forceinline__ float bf2f(short s) { return __uint_as_float(((unsigned)(unsigned short)s) << 16); }
; __device__ __forceinline__ bf16x8 tobf8(f32x8 x) { u32x4 w = {cvtpk(x[0], x[1]), cvtpk(x[2], x[3]), cvtpk(x[4], x[5]), cvtpk(x[6], x[7])}; return *reinterpret_cast<bf16x8*>(&w); }
; __device__ __forceinline__ int v_st(int k, int c) { const int kk = (k & ~0xC) | ((k & 4) << 1) | ((k & 8) >> 1); return ((kk >> 3) * 4 + (c >> 5)) * 512 + ((kk & 7) * 32 + (c & 31)) * 2; }
; __device__ __forceinline__ void spatial_phase(const Params& p, char* lds) {
;     ...
;         for (int q = 0; q < 4; ++q) { const int st_ = q >> 1, ch_ = q & 1; if (samp && st_ == 1) continue;
; #pragma unroll
;             for (int hf = 0; hf < 2; ++hf) { const int k = sr + 32 * hf, s = st_ * 64 + k; const int cc = ch_ * 128 + sc;
;                 bf16x8 w = {};
;                 if (s < nrows) { const float mu = mu_[st_ * 2 + hf], rs = rs_[st_ * 2 + hf];
;                     const bf16x8 rw = raw[q * 2 + hf];
;                     const f32x4 g0 = *(const f32x4*)(p.ln_g + g * GD + cc), g1 = *(const f32x4*)(p.ln_g + g * GD + cc + 4), b0 = *(const f32x4*)(p.ln_b + g * GD + cc), b1 = *(const f32x4*)(p.ln_b + g * GD + cc + 4);
;                     f32x8 y;
; #pragma unroll
;                     for (int i = 0; i < 4; ++i) { y[i] = (bf2f(rw[i]) - mu) * rs * g0[i] + b0[i]; y[4 + i] = (bf2f(rw[4 + i]) - mu) * rs * g1[i] + b1[i]; }
;                     if (samp) { float* d = p.out + O_SGV + (size_t)(cidx * TS + s) * CW + g * GD + cc; __builtin_nontemporal_store((f32x4){y[0], y[1], y[2], y[3]}, (f32x4*)d); __builtin_nontemporal_store((f32x4){y[4], y[5], y[6], y[7]}, (f32x4*)(d + 4)); }
;                     w = tobf8(y); }
;                 *(bf16x8*)(lds + q * 16384 + v_st(k, sc)) = w; } }
.LBB0_1215:
	s_or_b64 exec, exec, s[44:45]
	ds_write_b128 v234, v[0:3]
	v_cmp_gt_u32_e64 s[44:45], s59, v200
	v_mov_b32_e32 v3, 0
	v_mov_b32_e32 v2, 0
	v_mov_b32_e32 v1, 0
	v_mov_b32_e32 v0, 0
	s_and_saveexec_b64 s[72:73], s[44:45]
	s_cbranch_execz .LBB0_1219
	s_lshl_b32 s74, s80, 2
	v_lshl_add_u64 v[0:1], v[220:221], 0, s[74:75]
	v_lshl_add_u64 v[12:13], v[222:223], 0, s[74:75]
	s_nop 0
	s_nop 0
	s_nop 0
	v_and_b32_e32 v17, 0xffff0000, v68
	v_lshlrev_b32_e32 v16, 16, v68
	v_pk_add_f32 v[16:17], v[16:17], v[184:185] op_sel_hi:[1,0] neg_lo:[0,1] neg_hi:[0,1]
	s_and_b64 vcc, exec, s[40:41]
	v_pk_mul_f32 v[16:17], v[16:17], v[194:195] op_sel_hi:[1,0]
	v_mov_b32_e32 v4, v36
	v_mov_b32_e32 v5, v37
	v_mov_b32_e32 v6, v38
	v_mov_b32_e32 v7, v39
	v_mov_b32_e32 v0, v32
	v_mov_b32_e32 v1, v33
	v_mov_b32_e32 v2, v34
	v_mov_b32_e32 v3, v35
	v_mov_b32_e32 v8, v44
	v_mov_b32_e32 v9, v45
	v_mov_b32_e32 v10, v46
	v_mov_b32_e32 v11, v47
	v_mov_b32_e32 v12, v40
	v_mov_b32_e32 v13, v41
	v_mov_b32_e32 v14, v42
	v_mov_b32_e32 v15, v43
	v_pk_fma_f32 v[0:1], v[16:17], v[0:1], v[12:13]
	v_and_b32_e32 v13, 0xffff0000, v70
	v_lshlrev_b32_e32 v12, 16, v70
	v_pk_add_f32 v[12:13], v[12:13], v[184:185] op_sel_hi:[1,0] neg_lo:[0,1] neg_hi:[0,1]
	s_nop 0
	v_pk_mul_f32 v[12:13], v[12:13], v[194:195] op_sel_hi:[1,0]
	s_nop 0
	v_pk_fma_f32 v[4:5], v[12:13], v[4:5], v[8:9]
	v_and_b32_e32 v9, 0xffff0000, v69
	v_lshlrev_b32_e32 v8, 16, v69
	v_pk_add_f32 v[8:9], v[8:9], v[184:185] op_sel_hi:[1,0] neg_lo:[0,1] neg_hi:[0,1]
	s_nop 0
	v_pk_mul_f32 v[8:9], v[8:9], v[194:195] op_sel_hi:[1,0]
	s_nop 0
	v_pk_fma_f32 v[2:3], v[8:9], v[2:3], v[14:15]
	v_and_b32_e32 v9, 0xffff0000, v71
	v_lshlrev_b32_e32 v8, 16, v71
	v_pk_add_f32 v[8:9], v[8:9], v[184:185] op_sel_hi:[1,0] neg_lo:[0,1] neg_hi:[0,1]
	s_nop 0
	v_pk_mul_f32 v[8:9], v[8:9], v[194:195] op_sel_hi:[1,0]
	s_nop 0
	v_pk_fma_f32 v[6:7], v[8:9], v[6:7], v[10:11]
	s_cbranch_vccnz .LBB0_1218
	v_add_u32_e32 v8, s58, v200
	v_ashrrev_i32_e32 v9, 31, v8
	v_lshlrev_b64 v[8:9], 14, v[8:9]
	v_lshl_add_u64 v[8:9], s[62:63], 0, v[8:9]
	v_lshl_add_u64 v[8:9], v[8:9], 0, s[74:75]
	v_lshlrev_b32_e32 v10, 2, v182
	v_mov_b32_e32 v11, v96
	v_lshl_add_u64 v[8:9], v[8:9], 0, v[10:11]
	global_store_dwordx4 v[8:9], v[0:3], off nt
	global_store_dwordx4 v[8:9], v[4:7], off offset:16 nt

; __device__ __forceinline__ float bf2f(short s) { return __uint_as_float(((unsigned)(unsigned short)s) << 16); }
; __device__ __forceinline__ bf16x8 tobf8(f32x8 x) { u32x4 w = {cvtpk(x[0], x[1]), cvtpk(x[2], x[3]), cvtpk(x[4], x[5]), cvtpk(x[6], x[7])}; return *reinterpret_cast<bf16x8*>(&w); }
; __device__ __forceinline__ int v_st(int k, int c) { const int kk = (k & ~0xC) | ((k & 4) << 1) | ((k & 8) >> 1); return ((kk >> 3) * 4 + (c >> 5)) * 512 + ((kk & 7) * 32 + (c & 31)) * 2; }
; __device__ __forceinline__ void spatial_phase(const Params& p, char* lds) {
;     ...
;         for (int q = 0; q < 4; ++q) { const int st_ = q >> 1, ch_ = q & 1; if (samp && st_ == 1) continue;
; #pragma unroll
;             for (int hf = 0; hf < 2; ++hf) { const int k = sr + 32 * hf, s = st_ * 64 + k; const int cc = ch_ * 128 + sc;
;                 bf16x8 w = {};
;                 if (s < nrows) { const float mu = mu_[st_ * 2 + hf], rs = rs_[st_ * 2 + hf];
;                     const bf16x8 rw = raw[q * 2 + hf];
;                     const f32x4 g0 = *(const f32x4*)(p.ln_g + g * GD + cc), g1 = *(const f32x4*)(p.ln_g + g * GD + cc + 4), b0 = *(const f32x4*)(p.ln_b + g * GD + cc), b1 = *(const f32x4*)(p.ln_b + g * GD + cc + 4);
;                     f32x8 y;
; #pragma unroll
;                     for (int i = 0; i < 4; ++i) { y[i] = (bf2f(rw[i]) - mu) * rs * g0[i] + b0[i]; y[4 + i] = (bf2f(rw[4 + i]) - mu) * rs * g1[i] + b1[i]; }
;                     if (samp) { float* d = p.out + O_SGV + (size_t)(cidx * TS + s) * CW + g * GD + cc; __builtin_nontemporal_store((f32x4){y[0], y[1], y[2], y[3]}, (f32x4*)d); __builtin_nontemporal_store((f32x4){y[4], y[5], y[6], y[7]}, (f32x4*)(d + 4)); }
;                     w = tobf8(y); }
;                 *(bf16x8*)(lds + q * 16384 + v_st(k, sc)) = w; } }
.LBB0_1219:
	s_or_b64 exec, exec, s[72:73]
	ds_write_b128 v235, v[0:3]
	v_mov_b32_e32 v3, 0
	v_mov_b32_e32 v2, 0
	v_mov_b32_e32 v1, 0
	v_mov_b32_e32 v0, 0
	s_and_saveexec_b64 s[72:73], s[42:43]
	s_cbranch_execz .LBB0_1223
	s_lshl_b32 s74, s80, 2
	v_lshl_add_u64 v[0:1], v[220:221], 0, s[74:75]
	v_lshl_add_u64 v[12:13], v[222:223], 0, s[74:75]
	s_nop 0
	s_nop 0
	s_nop 0
	v_and_b32_e32 v17, 0xffff0000, v72
	v_lshlrev_b32_e32 v16, 16, v72
	v_pk_add_f32 v[16:17], v[16:17], v[186:187] op_sel_hi:[1,0] neg_lo:[0,1] neg_hi:[0,1]
	s_and_b64 vcc, exec, s[40:41]
	v_pk_mul_f32 v[16:17], v[16:17], v[98:99] op_sel_hi:[1,0]
	v_mov_b32_e32 v4, v52
	v_mov_b32_e32 v5, v53
	v_mov_b32_e32 v6, v54
	v_mov_b32_e32 v7, v55
	v_mov_b32_e32 v0, v48
	v_mov_b32_e32 v1, v49
	v_mov_b32_e32 v2, v50
	v_mov_b32_e32 v3, v51
	v_mov_b32_e32 v8, v60
	v_mov_b32_e32 v9, v61
	v_mov_b32_e32 v10, v62
	v_mov_b32_e32 v11, v63
	v_mov_b32_e32 v12, v56
	v_mov_b32_e32 v13, v57
	v_mov_b32_e32 v14, v58
	v_mov_b32_e32 v15, v59
	v_pk_fma_f32 v[0:1], v[16:17], v[0:1], v[12:13]
	v_and_b32_e32 v13, 0xffff0000, v74
	v_lshlrev_b32_e32 v12, 16, v74
	v_pk_add_f32 v[12:13], v[12:13], v[186:187] op_sel_hi:[1,0] neg_lo:[0,1] neg_hi:[0,1]
	s_nop 0
	v_pk_mul_f32 v[12:13], v[12:13], v[98:99] op_sel_hi:[1,0]
	s_nop 0
	v_pk_fma_f32 v[4:5], v[12:13], v[4:5], v[8:9]
	v_and_b32_e32 v9, 0xffff0000, v73
	v_lshlrev_b32_e32 v8, 16, v73
	v_pk_add_f32 v[8:9], v[8:9], v[186:187] op_sel_hi:[1,0] neg_lo:[0,1] neg_hi:[0,1]
	s_nop 0
	v_pk_mul_f32 v[8:9], v[8:9], v[98:99] op_sel_hi:[1,0]
	s_nop 0
	v_pk_fma_f32 v[2:3], v[8:9], v[2:3], v[14:15]
	v_and_b32_e32 v9, 0xffff0000, v75
	v_lshlrev_b32_e32 v8, 16, v75
	v_pk_add_f32 v[8:9], v[8:9], v[186:187] op_sel_hi:[1,0] neg_lo:[0,1] neg_hi:[0,1]
	s_nop 0
	v_pk_mul_f32 v[8:9], v[8:9], v[98:99] op_sel_hi:[1,0]
	s_nop 0
	v_pk_fma_f32 v[6:7], v[8:9], v[6:7], v[10:11]
	s_cbranch_vccnz .LBB0_1222
	v_add_u32_e32 v8, s58, v180
	v_ashrrev_i32_e32 v9, 31, v8
	v_lshlrev_b64 v[8:9], 14, v[8:9]
	v_lshl_add_u64 v[8:9], s[62:63], 0, v[8:9]
	v_lshl_add_u64 v[8:9], v[8:9], 0, s[74:75]
	v_lshlrev_b32_e32 v10, 2, v182
	v_mov_b32_e32 v11, v96
	v_lshl_add_u64 v[8:9], v[8:9], 0, v[10:11]
	global_store_dwordx4 v[8:9], v[0:3], off offset:512 nt
	global_store_dwordx4 v[8:9], v[4:7], off offset:528 nt

; __device__ __forceinline__ float bf2f(short s) { return __uint_as_float(((unsigned)(unsigned short)s) << 16); }
; __device__ __forceinline__ bf16x8 tobf8(f32x8 x) { u32x4 w = {cvtpk(x[0], x[1]), cvtpk(x[2], x[3]), cvtpk(x[4], x[5]), cvtpk(x[6], x[7])}; return *reinterpret_cast<bf16x8*>(&w); }
; __device__ __forceinline__ int v_st(int k, int c) { const int kk = (k & ~0xC) | ((k & 4) << 1) | ((k & 8) >> 1); return ((kk >> 3) * 4 + (c >> 5)) * 512 + ((kk & 7) * 32 + (c & 31)) * 2; }
; __device__ __forceinline__ void spatial_phase(const Params& p, char* lds) {
;     ...
;         for (int q = 0; q < 4; ++q) { const int st_ = q >> 1, ch_ = q & 1; if (samp && st_ == 1) continue;
; #pragma unroll
;             for (int hf = 0; hf < 2; ++hf) { const int k = sr + 32 * hf, s = st_ * 64 + k; const int cc = ch_ * 128 + sc;
;                 bf16x8 w = {};
;                 if (s < nrows) { const float mu = mu_[st_ * 2 + hf], rs = rs_[st_ * 2 + hf];
;                     const bf16x8 rw = raw[q * 2 + hf];
;                     const f32x4 g0 = *(const f32x4*)(p.ln_g + g * GD + cc), g1 = *(const f32x4*)(p.ln_g + g * GD + cc + 4), b0 = *(const f32x4*)(p.ln_b + g * GD + cc), b1 = *(const f32x4*)(p.ln_b + g * GD + cc + 4);
;                     f32x8 y;
; #pragma unroll
;                     for (int i = 0; i < 4; ++i) { y[i] = (bf2f(rw[i]) - mu) * rs * g0[i] + b0[i]; y[4 + i] = (bf2f(rw[4 + i]) - mu) * rs * g1[i] + b1[i]; }
;                     if (samp) { float* d = p.out + O_SGV + (size_t)(cidx * TS + s) * CW + g * GD + cc; __builtin_nontemporal_store((f32x4){y[0], y[1], y[2], y[3]}, (f32x4*)d); __builtin_nontemporal_store((f32x4){y[4], y[5], y[6], y[7]}, (f32x4*)(d + 4)); }
;                     w = tobf8(y); }
;                 *(bf16x8*)(lds + q * 16384 + v_st(k, sc)) = w; } }
.LBB0_1223:
	s_or_b64 exec, exec, s[72:73]
	ds_write_b128 v234, v[0:3] offset:16384
	v_mov_b32_e32 v3, 0
	v_mov_b32_e32 v2, 0
	v_mov_b32_e32 v1, 0
	v_mov_b32_e32 v0, 0
	s_and_saveexec_b64 s[42:43], s[44:45]
	s_cbranch_execz .LBB0_1227
	s_lshl_b32 s74, s80, 2
	v_lshl_add_u64 v[0:1], v[220:221], 0, s[74:75]
	v_lshl_add_u64 v[12:13], v[222:223], 0, s[74:75]
	s_nop 0
	s_nop 0
	s_nop 0
	v_and_b32_e32 v17, 0xffff0000, v76
	v_lshlrev_b32_e32 v16, 16, v76
	v_pk_add_f32 v[16:17], v[16:17], v[184:185] op_sel_hi:[1,0] neg_lo:[0,1] neg_hi:[0,1]
	s_and_b64 vcc, exec, s[40:41]
	v_pk_mul_f32 v[16:17], v[16:17], v[194:195] op_sel_hi:[1,0]
	v_mov_b32_e32 v4, v52
	v_mov_b32_e32 v5, v53
	v_mov_b32_e32 v6, v54
	v_mov_b32_e32 v7, v55
	v_mov_b32_e32 v0, v48
	v_mov_b32_e32 v1, v49
	v_mov_b32_e32 v2, v50
	v_mov_b32_e32 v3, v51
	v_mov_b32_e32 v8, v60
	v_mov_b32_e32 v9, v61
	v_mov_b32_e32 v10, v62
	v_mov_b32_e32 v11, v63
	v_mov_b32_e32 v12, v56
	v_mov_b32_e32 v13, v57
	v_mov_b32_e32 v14, v58
	v_mov_b32_e32 v15, v59
	v_pk_fma_f32 v[0:1], v[16:17], v[0:1], v[12:13]
	v_and_b32_e32 v13, 0xffff0000, v78
	v_lshlrev_b32_e32 v12, 16, v78
	v_pk_add_f32 v[12:13], v[12:13], v[184:185] op_sel_hi:[1,0] neg_lo:[0,1] neg_hi:[0,1]
	s_nop 0
	v_pk_mul_f32 v[12:13], v[12:13], v[194:195] op_sel_hi:[1,0]
	s_nop 0
	v_pk_fma_f32 v[4:5], v[12:13], v[4:5], v[8:9]
	v_and_b32_e32 v9, 0xffff0000, v77
	v_lshlrev_b32_e32 v8, 16, v77
	v_pk_add_f32 v[8:9], v[8:9], v[184:185] op_sel_hi:[1,0] neg_lo:[0,1] neg_hi:[0,1]
	s_nop 0
	v_pk_mul_f32 v[8:9], v[8:9], v[194:195] op_sel_hi:[1,0]
	s_nop 0
	v_pk_fma_f32 v[2:3], v[8:9], v[2:3], v[14:15]
	v_and_b32_e32 v9, 0xffff0000, v79
	v_lshlrev_b32_e32 v8, 16, v79
	v_pk_add_f32 v[8:9], v[8:9], v[184:185] op_sel_hi:[1,0] neg_lo:[0,1] neg_hi:[0,1]
	s_nop 0
	v_pk_mul_f32 v[8:9], v[8:9], v[194:195] op_sel_hi:[1,0]
	s_nop 0
	v_pk_fma_f32 v[6:7], v[8:9], v[6:7], v[10:11]
	s_cbranch_vccnz .LBB0_1226
	v_add_u32_e32 v8, s58, v200
	v_ashrrev_i32_e32 v9, 31, v8
	v_lshlrev_b64 v[8:9], 14, v[8:9]
	v_lshl_add_u64 v[8:9], s[62:63], 0, v[8:9]
	v_lshl_add_u64 v[8:9], v[8:9], 0, s[74:75]
	v_lshlrev_b32_e32 v10, 2, v182
	v_mov_b32_e32 v11, v96
	v_lshl_add_u64 v[8:9], v[8:9], 0, v[10:11]
	global_store_dwordx4 v[8:9], v[0:3], off offset:512 nt
	global_store_dwordx4 v[8:9], v[4:7], off offset:528 nt

; __device__ __forceinline__ float bf2f(short s) { return __uint_as_float(((unsigned)(unsigned short)s) << 16); }
; __device__ __forceinline__ bf16x8 tobf8(f32x8 x) { u32x4 w = {cvtpk(x[0], x[1]), cvtpk(x[2], x[3]), cvtpk(x[4], x[5]), cvtpk(x[6], x[7])}; return *reinterpret_cast<bf16x8*>(&w); }
; __device__ __forceinline__ int v_st(int k, int c) { const int kk = (k & ~0xC) | ((k & 4) << 1) | ((k & 8) >> 1); return ((kk >> 3) * 4 + (c >> 5)) * 512 + ((kk & 7) * 32 + (c & 31)) * 2; }
; __device__ __forceinline__ void spatial_phase(const Params& p, char* lds) {
;     ...
;         for (int q = 0; q < 4; ++q) { const int st_ = q >> 1, ch_ = q & 1; if (samp && st_ == 1) continue;
; #pragma unroll
;             for (int hf = 0; hf < 2; ++hf) { const int k = sr + 32 * hf, s = st_ * 64 + k; const int cc = ch_ * 128 + sc;
;                 bf16x8 w = {};
;                 if (s < nrows) { const float mu = mu_[st_ * 2 + hf], rs = rs_[st_ * 2 + hf];
;                     const bf16x8 rw = raw[q * 2 + hf];
;                     const f32x4 g0 = *(const f32x4*)(p.ln_g + g * GD + cc), g1 = *(const f32x4*)(p.ln_g + g * GD + cc + 4), b0 = *(const f32x4*)(p.ln_b + g * GD + cc), b1 = *(const f32x4*)(p.ln_b + g * GD + cc + 4);
;                     f32x8 y;
; #pragma unroll
;                     for (int i = 0; i < 4; ++i) { y[i] = (bf2f(rw[i]) - mu) * rs * g0[i] + b0[i]; y[4 + i] = (bf2f(rw[4 + i]) - mu) * rs * g1[i] + b1[i]; }
;                     if (samp) { float* d = p.out + O_SGV + (size_t)(cidx * TS + s) * CW + g * GD + cc; __builtin_nontemporal_store((f32x4){y[0], y[1], y[2], y[3]}, (f32x4*)d); __builtin_nontemporal_store((f32x4){y[4], y[5], y[6], y[7]}, (f32x4*)(d + 4)); }
;                     w = tobf8(y); }
;                 *(bf16x8*)(lds + q * 16384 + v_st(k, sc)) = w; } }
.LBB0_1227:
	s_or_b64 exec, exec, s[42:43]
	s_and_b64 vcc, exec, s[38:39]
	ds_write_b128 v235, v[0:3] offset:16384
	s_cbranch_vccnz .LBB0_1233
	s_lshl_b32 s74, s80, 2
	v_lshl_add_u64 v[8:9], v[222:223], 0, s[74:75]
	v_lshl_add_u64 v[6:7], v[220:221], 0, s[74:75]
	v_and_b32_e32 v5, 0xffff0000, v80
	v_sub_f32_e32 v5, v5, v197
	v_mul_f32_e32 v5, v5, v99
	v_lshlrev_b32_e32 v4, 16, v80
	v_sub_f32_e32 v4, v4, v197
	v_mul_f32_e32 v4, v4, v99
	v_mov_b32_e32 v0, v44
	v_mov_b32_e32 v1, v45
	v_mov_b32_e32 v2, v46
	v_mov_b32_e32 v3, v47
	v_mov_b32_e32 v10, v40
	v_mov_b32_e32 v11, v41
	v_mov_b32_e32 v12, v42
	v_mov_b32_e32 v13, v43
	v_mov_b32_e32 v14, v36
	v_mov_b32_e32 v15, v37
	v_mov_b32_e32 v16, v38
	v_mov_b32_e32 v17, v39
	v_mov_b32_e32 v18, v32
	v_mov_b32_e32 v19, v33
	v_mov_b32_e32 v20, v34
	v_mov_b32_e32 v21, v35
	v_fma_f32 v5, v5, v19, v11
	v_and_b32_e32 v11, 0xffff0000, v81
	v_sub_f32_e32 v11, v11, v197
	v_mul_f32_e32 v11, v11, v99
	v_fmac_f32_e32 v13, v11, v21
	v_lshlrev_b32_e32 v11, 16, v82
	v_sub_f32_e32 v11, v11, v197
	v_mul_f32_e32 v11, v11, v99
	v_fma_f32 v4, v4, v18, v10
	v_lshlrev_b32_e32 v10, 16, v81
	v_fma_f32 v11, v11, v14, v0
	v_and_b32_e32 v0, 0xffff0000, v82
	v_sub_f32_e32 v10, v10, v197
	v_sub_f32_e32 v0, v0, v197
	v_mul_f32_e32 v10, v10, v99
	v_mul_f32_e32 v0, v0, v99
	v_fma_f32 v10, v10, v20, v12
	v_fma_f32 v12, v0, v15, v1
	v_lshlrev_b32_e32 v0, 16, v83
	v_sub_f32_e32 v0, v0, v197
	v_mul_f32_e32 v0, v0, v99
	v_fma_f32 v14, v0, v16, v2
	v_and_b32_e32 v0, 0xffff0000, v83
	v_sub_f32_e32 v0, v0, v197
	v_mul_f32_e32 v0, v0, v99
	v_fmac_f32_e32 v3, v0, v17
	v_cvt_pk_bf16_f32 v0, v4, v5
	v_cvt_pk_bf16_f32 v1, v10, v13
	v_cvt_pk_bf16_f32 v2, v11, v12
	v_cvt_pk_bf16_f32 v3, v14, v3
	ds_write_b128 v234, v[0:3] offset:32768
	v_mov_b32_e32 v0, 0
	v_mov_b32_e32 v2, 0
	v_mov_b32_e32 v3, 0
	v_mov_b32_e32 v4, 0
	v_mov_b32_e32 v5, 0
	s_and_saveexec_b64 s[40:41], s[36:37]
	s_cbranch_execz .LBB0_1230
	v_lshlrev_b32_e32 v1, 16, v84
	v_sub_f32_e32 v1, v1, v199
	v_mul_f32_e32 v1, v1, v97
	v_mov_b32_e32 v2, v44
	v_mov_b32_e32 v3, v45
	v_mov_b32_e32 v4, v46
	v_mov_b32_e32 v5, v47
	v_mov_b32_e32 v10, v40
	v_mov_b32_e32 v11, v41
	v_mov_b32_e32 v12, v42
	v_mov_b32_e32 v13, v43
	v_mov_b32_e32 v14, v36
	v_mov_b32_e32 v15, v37
	v_mov_b32_e32 v16, v38
	v_mov_b32_e32 v17, v39
	v_mov_b32_e32 v18, v32
	v_mov_b32_e32 v19, v33
	v_mov_b32_e32 v20, v34
	v_mov_b32_e32 v21, v35
	v_fma_f32 v1, v1, v18, v10
	v_and_b32_e32 v10, 0xffff0000, v84
	v_sub_f32_e32 v10, v10, v199
	v_mul_f32_e32 v10, v10, v97
	v_fma_f32 v10, v10, v19, v11
	v_lshlrev_b32_e32 v11, 16, v85
	v_sub_f32_e32 v11, v11, v199
	v_mul_f32_e32 v11, v11, v97
	v_fma_f32 v11, v11, v20, v12
	v_and_b32_e32 v12, 0xffff0000, v85
	v_sub_f32_e32 v12, v12, v199
	v_mul_f32_e32 v12, v12, v97
	v_fmac_f32_e32 v13, v12, v21
	v_lshlrev_b32_e32 v12, 16, v86
	v_sub_f32_e32 v12, v12, v199
	v_mul_f32_e32 v12, v12, v97
	v_fma_f32 v12, v12, v14, v2
	v_and_b32_e32 v2, 0xffff0000, v86
	v_sub_f32_e32 v2, v2, v199
	v_mul_f32_e32 v2, v2, v97
	v_fma_f32 v14, v2, v15, v3
	v_lshlrev_b32_e32 v2, 16, v87
	v_sub_f32_e32 v2, v2, v199
	v_mul_f32_e32 v2, v2, v97
	v_fma_f32 v15, v2, v16, v4
	v_and_b32_e32 v2, 0xffff0000, v87
	v_sub_f32_e32 v2, v2, v199
	v_mul_f32_e32 v2, v2, v97
	v_fmac_f32_e32 v5, v2, v17
	v_cvt_pk_bf16_f32 v2, v1, v10
	v_cvt_pk_bf16_f32 v3, v11, v13
	v_cvt_pk_bf16_f32 v4, v12, v14
	v_cvt_pk_bf16_f32 v5, v15, v5
.LBB0_1230:
	s_or_b64 exec, exec, s[40:41]
	ds_write_b128 v235, v[2:5] offset:32768
	v_lshlrev_b32_e32 v1, 16, v88
	v_sub_f32_e32 v1, v1, v197
	v_mul_f32_e32 v1, v1, v99
	v_mov_b32_e32 v2, v60
	v_mov_b32_e32 v3, v61
	v_mov_b32_e32 v4, v62
	v_mov_b32_e32 v5, v63
	v_mov_b32_e32 v10, v56
	v_mov_b32_e32 v11, v57
	v_mov_b32_e32 v12, v58
	v_mov_b32_e32 v13, v59
	v_mov_b32_e32 v14, v52
	v_mov_b32_e32 v15, v53
	v_mov_b32_e32 v16, v54
	v_mov_b32_e32 v17, v55
	v_mov_b32_e32 v18, v48
	v_mov_b32_e32 v19, v49
	v_mov_b32_e32 v20, v50
	v_mov_b32_e32 v21, v51
	v_fma_f32 v1, v1, v18, v10
	v_and_b32_e32 v10, 0xffff0000, v88
	v_sub_f32_e32 v10, v10, v197
	v_mul_f32_e32 v10, v10, v99
	v_fma_f32 v10, v10, v19, v11
	v_lshlrev_b32_e32 v11, 16, v89
	v_sub_f32_e32 v11, v11, v197
	v_mul_f32_e32 v11, v11, v99
	v_fma_f32 v11, v11, v20, v12
	v_and_b32_e32 v12, 0xffff0000, v89
	v_sub_f32_e32 v12, v12, v197
	v_mul_f32_e32 v12, v12, v99
	v_fmac_f32_e32 v13, v12, v21
	v_lshlrev_b32_e32 v12, 16, v90
	v_sub_f32_e32 v12, v12, v197
	v_mul_f32_e32 v12, v12, v99
	v_fma_f32 v12, v12, v14, v2
	v_and_b32_e32 v2, 0xffff0000, v90
	v_sub_f32_e32 v2, v2, v197
	v_mul_f32_e32 v2, v2, v99
	v_fma_f32 v14, v2, v15, v3
	v_lshlrev_b32_e32 v2, 16, v91
	v_sub_f32_e32 v2, v2, v197
	v_mul_f32_e32 v2, v2, v99
	v_fma_f32 v15, v2, v16, v4
	v_and_b32_e32 v2, 0xffff0000, v91
	v_sub_f32_e32 v2, v2, v197
	v_mul_f32_e32 v2, v2, v99
	v_fmac_f32_e32 v5, v2, v17
	v_cvt_pk_bf16_f32 v2, v1, v10
	v_cvt_pk_bf16_f32 v3, v11, v13
	v_cvt_pk_bf16_f32 v4, v12, v14
	v_cvt_pk_bf16_f32 v5, v15, v5
	ds_write_b128 v234, v[2:5] offset:49152
	v_mov_b32_e32 v1, 0
	v_mov_b32_e32 v2, 0
	v_mov_b32_e32 v3, 0
	s_and_saveexec_b64 s[40:41], s[36:37]
	s_cbranch_execz .LBB0_1232
	s_nop 0
	s_nop 0
	s_nop 0
	v_and_b32_e32 v16, 0xffff0000, v95
	v_sub_f32_e32 v16, v16, v199
	v_mul_f32_e32 v16, v16, v97
	v_mov_b32_e32 v0, v56
	v_mov_b32_e32 v1, v57
	v_mov_b32_e32 v2, v58
	v_mov_b32_e32 v3, v59
	v_mov_b32_e32 v8, v60
	v_mov_b32_e32 v9, v61
	v_mov_b32_e32 v10, v62
	v_mov_b32_e32 v11, v63
	v_mov_b32_e32 v12, v48
	v_mov_b32_e32 v13, v49
	v_mov_b32_e32 v14, v50
	v_mov_b32_e32 v15, v51
	v_mov_b32_e32 v4, v52
	v_mov_b32_e32 v5, v53
	v_mov_b32_e32 v6, v54
	v_mov_b32_e32 v7, v55
	v_fma_f32 v7, v16, v7, v11
	v_lshlrev_b32_e32 v11, 16, v95
	v_sub_f32_e32 v11, v11, v199
	v_mul_f32_e32 v11, v11, v97
	v_fma_f32 v6, v11, v6, v10
	v_and_b32_e32 v10, 0xffff0000, v94
	v_sub_f32_e32 v10, v10, v199
	v_mul_f32_e32 v10, v10, v97
	v_fma_f32 v5, v10, v5, v9
	v_lshlrev_b32_e32 v9, 16, v94
	v_sub_f32_e32 v9, v9, v199
	v_mul_f32_e32 v9, v9, v97
	v_fmac_f32_e32 v8, v9, v4
	v_and_b32_e32 v4, 0xffff0000, v93
	v_sub_f32_e32 v4, v4, v199
	v_mul_f32_e32 v4, v4, v97
	v_fma_f32 v3, v4, v15, v3
	v_lshlrev_b32_e32 v4, 16, v93
	v_sub_f32_e32 v4, v4, v199
	v_mul_f32_e32 v4, v4, v97
	v_fma_f32 v2, v4, v14, v2
	v_and_b32_e32 v4, 0xffff0000, v92
	v_sub_f32_e32 v4, v4, v199
	v_mul_f32_e32 v4, v4, v97
	v_fma_f32 v1, v4, v13, v1
	v_lshlrev_b32_e32 v4, 16, v92
	v_sub_f32_e32 v4, v4, v199
	v_mul_f32_e32 v4, v4, v97
	v_fmac_f32_e32 v0, v4, v12
	v_cvt_pk_bf16_f32 v0, v0, v1
	v_cvt_pk_bf16_f32 v1, v2, v3
	v_cvt_pk_bf16_f32 v2, v8, v5
	v_cvt_pk_bf16_f32 v3, v6, v7

; __global__ void __launch_bounds__(512, 2) mega_fwd(Params p) {
	.amdhsa_kernel _Z8mega_fwd6Params
		.amdhsa_group_segment_fixed_size 0
		.amdhsa_private_segment_fixed_size 0
		.amdhsa_kernarg_size 432
		.amdhsa_user_sgpr_count 2
		.amdhsa_user_sgpr_dispatch_ptr 0
		.amdhsa_user_sgpr_queue_ptr 0
		.amdhsa_user_sgpr_kernarg_segment_ptr 1
		.amdhsa_user_sgpr_dispatch_id 0
		.amdhsa_user_sgpr_kernarg_preload_length 0
		.amdhsa_user_sgpr_kernarg_preload_offset 0
		.amdhsa_user_sgpr_private_segment_size 0
		.amdhsa_uses_dynamic_stack 0
		.amdhsa_enable_private_segment 0
		.amdhsa_system_sgpr_workgroup_id_x 1
		.amdhsa_system_sgpr_workgroup_id_y 0
		.amdhsa_system_sgpr_workgroup_id_z 0
		.amdhsa_system_sgpr_workgroup_info 0
		.amdhsa_system_vgpr_workitem_id 2
		.amdhsa_next_free_vgpr 256
		.amdhsa_next_free_sgpr 102
		.amdhsa_accum_offset 256
		.amdhsa_reserve_vcc 1
		.amdhsa_float_round_mode_32 0
		.amdhsa_float_round_mode_16_64 0
		.amdhsa_float_denorm_mode_32 3
		.amdhsa_float_denorm_mode_16_64 3
		.amdhsa_dx10_clamp 1
		.amdhsa_ieee_mode 1
		.amdhsa_fp16_overflow 0
		.amdhsa_tg_split 0
		.amdhsa_exception_fp_ieee_invalid_op 0
		.amdhsa_exception_fp_denorm_src 0
		.amdhsa_exception_fp_ieee_div_zero 0
		.amdhsa_exception_fp_ieee_overflow 0
		.amdhsa_exception_fp_ieee_underflow 0
		.amdhsa_exception_fp_ieee_inexact 0
		.amdhsa_exception_int_div_zero 0
	.end_amdhsa_kernel

; __global__ void __launch_bounds__(512, 2) mega_fwd(Params p) {
amdhsa.kernels:
  - .agpr_count:     0
    .args:
      - .offset:         0
        .size:           176
        .value_kind:     by_value
      - .offset:         176
        .size:           4
        .value_kind:     hidden_block_count_x
      - .offset:         180
        .size:           4
        .value_kind:     hidden_block_count_y
      - .offset:         184
        .size:           4
        .value_kind:     hidden_block_count_z
      - .offset:         188
        .size:           2
        .value_kind:     hidden_group_size_x
      - .offset:         190
        .size:           2
        .value_kind:     hidden_group_size_y
      - .offset:         192
        .size:           2
        .value_kind:     hidden_group_size_z
      - .offset:         194
        .size:           2
        .value_kind:     hidden_remainder_x
      - .offset:         196
        .size:           2
        .value_kind:     hidden_remainder_y
      - .offset:         198
        .size:           2
        .value_kind:     hidden_remainder_z
      - .offset:         216
        .size:           8
        .value_kind:     hidden_global_offset_x
      - .offset:         224
        .size:           8
        .value_kind:     hidden_global_offset_y
      - .offset:         232
        .size:           8
        .value_kind:     hidden_global_offset_z
      - .offset:         240
        .size:           2
        .value_kind:     hidden_grid_dims
      - .offset:         264
        .size:           8
        .value_kind:     hidden_multigrid_sync_arg
      - .offset:         296
        .size:           4
        .value_kind:     hidden_dynamic_lds_size
    .group_segment_fixed_size: 0
    .kernarg_segment_align: 8
    .kernarg_segment_size: 432
    .language:       OpenCL C
    .language_version:
      - 2
      - 0
    .max_flat_workgroup_size: 512
    .name:           _Z8mega_fwd6Params
    .private_segment_fixed_size: 0
    .sgpr_count:     108
    .sgpr_spill_count: 192
    .symbol:         _Z8mega_fwd6Params.kd
    .uniform_work_group_size: 1
    .uses_dynamic_stack: false
    .vgpr_count:     256
    .vgpr_spill_count: 0
    .wavefront_size: 64
